# GEMM K-loops: flips deleted, static s_setprio 1 for the OLDER wave half (waves 0-3)
# speedup vs baseline: 1.0043x; 1.0043x over previous
;     __device__ __forceinline__ bool next(int i, pg8::Unit& u) const { if (c < 128 || i >= 2) return false; const int idx = (c - 128) * 2 + i; u.pm = idx >> 2; u.pn = idx & 3; return true; }
; template <class Epi, class Sched, bool ALIGN_EPI = false, bool SP2 = false, bool F16 = false>
; __device__ __forceinline__ void gemm_phase(PG8_LAS unsigned char* lds, const Gemm g, const Sched& S, const Epi& E, const int wid_in) {
;     ...
;         const bool has_next = S.next(ui + 1, nxt);
;         const char* nA = has_next ? (const char*)g.A + (size_t)nxt.pm * tstep : cA; const char* nB = has_next ? (const char*)g.Bt + (size_t)nxt.pn * tstep : cB;
;     ...
; #pragma unroll
;         for (int a = 0; a < 2; ++a)
; #pragma unroll
;             for (int b = 0; b < 2; ++b)
; #pragma unroll
;                 for (int m = 0; m < 4; ++m)
; #pragma unroll
;                     for (int n = 0; n < 2; ++n) acc[a][b][m][n] = (f32x4){0.f, 0.f, 0.f, 0.f};
;         cur = nxt; cA = nA; cB = nB; ++ui;
.LBB0_223:
	s_ashr_i32 s51, s50, 31
	s_lshl_b64 s[42:43], s[50:51], 19
	s_add_u32 s52, s79, s42
	s_addc_u32 s53, s80, s43
	s_and_b64 s[42:43], s[6:7], exec
	s_cselect_b32 s9, s53, s57
	s_cselect_b32 s21, s52, s56
	s_ashr_i32 s49, s48, 31
	s_lshl_b64 s[42:43], s[48:49], 19
	s_add_u32 s54, s81, s42
	s_addc_u32 s55, s82, s43
	s_and_b64 s[42:43], s[6:7], exec
	s_cselect_b32 s42, s55, s59
	s_cselect_b32 s43, s54, s58
	s_add_u32 s56, s56, 0x40080
	s_addc_u32 s57, s57, 0
	s_add_u32 s49, s58, 0x100
	v_mov_b32_e32 v0, 0
	s_addc_u32 s51, s59, 0
	s_mov_b32 s62, -2
	s_waitcnt lgkmcnt(0)
	v_mov_b32_e32 v1, v0
	v_mov_b32_e32 v2, v0
	v_mov_b32_e32 v3, v0
	v_mov_b32_e32 v4, v0
	v_mov_b32_e32 v5, v0
	v_mov_b32_e32 v6, v0
	v_mov_b32_e32 v7, v0
	v_mov_b32_e32 v16, v0
	v_mov_b32_e32 v17, v0
	v_mov_b32_e32 v18, v0
	v_mov_b32_e32 v19, v0
	v_mov_b32_e32 v20, v0
	v_mov_b32_e32 v21, v0
	v_mov_b32_e32 v22, v0
	v_mov_b32_e32 v23, v0
	v_mov_b32_e32 v32, v0
	v_mov_b32_e32 v33, v0
	v_mov_b32_e32 v34, v0
	v_mov_b32_e32 v35, v0
	v_mov_b32_e32 v36, v0
	v_mov_b32_e32 v37, v0
	v_mov_b32_e32 v38, v0
	v_mov_b32_e32 v39, v0
	v_mov_b32_e32 v48, v0
	v_mov_b32_e32 v49, v0
	v_mov_b32_e32 v50, v0
	v_mov_b32_e32 v51, v0
	v_mov_b32_e32 v52, v0
	v_mov_b32_e32 v53, v0
	v_mov_b32_e32 v54, v0
	v_mov_b32_e32 v55, v0
	v_mov_b32_e32 v8, v0
	v_mov_b32_e32 v9, v0
	v_mov_b32_e32 v10, v0
	v_mov_b32_e32 v11, v0
	v_mov_b32_e32 v12, v0
	v_mov_b32_e32 v13, v0
	v_mov_b32_e32 v14, v0
	v_mov_b32_e32 v15, v0
	v_mov_b32_e32 v24, v0
	v_mov_b32_e32 v25, v0
	v_mov_b32_e32 v26, v0
	v_mov_b32_e32 v27, v0
	v_mov_b32_e32 v28, v0
	v_mov_b32_e32 v29, v0
	v_mov_b32_e32 v30, v0
	v_mov_b32_e32 v31, v0
	v_mov_b32_e32 v40, v0
	v_mov_b32_e32 v41, v0
	v_mov_b32_e32 v42, v0
	v_mov_b32_e32 v43, v0
	v_mov_b32_e32 v44, v0
	v_mov_b32_e32 v45, v0
	v_mov_b32_e32 v46, v0
	v_mov_b32_e32 v47, v0
	v_mov_b32_e32 v56, v0
	v_mov_b32_e32 v57, v0
	v_mov_b32_e32 v58, v0
	v_mov_b32_e32 v59, v0
	v_mov_b32_e32 v60, v0
	v_mov_b32_e32 v61, v0
	v_mov_b32_e32 v62, v0
	v_mov_b32_e32 v63, v0
	v_mov_b32_e32 v64, v0
	v_mov_b32_e32 v65, v0
	v_mov_b32_e32 v66, v0
	v_mov_b32_e32 v67, v0
	v_mov_b32_e32 v68, v0
	v_mov_b32_e32 v69, v0
	v_mov_b32_e32 v70, v0
	v_mov_b32_e32 v71, v0
	v_mov_b32_e32 v80, v0
	v_mov_b32_e32 v81, v0
	v_mov_b32_e32 v82, v0
	v_mov_b32_e32 v83, v0
	v_mov_b32_e32 v84, v0
	v_mov_b32_e32 v85, v0
	v_mov_b32_e32 v86, v0
	v_mov_b32_e32 v87, v0
	v_mov_b32_e32 v96, v0
	v_mov_b32_e32 v97, v0
	v_mov_b32_e32 v98, v0
	v_mov_b32_e32 v99, v0
	v_mov_b32_e32 v100, v0
	v_mov_b32_e32 v101, v0
	v_mov_b32_e32 v102, v0
	v_mov_b32_e32 v103, v0
	v_mov_b32_e32 v112, v0
	v_mov_b32_e32 v113, v0
	v_mov_b32_e32 v114, v0
	v_mov_b32_e32 v115, v0
	v_mov_b32_e32 v116, v0
	v_mov_b32_e32 v117, v0
	v_mov_b32_e32 v118, v0
	v_mov_b32_e32 v119, v0
	v_mov_b32_e32 v72, v0
	v_mov_b32_e32 v73, v0
	v_mov_b32_e32 v74, v0
	v_mov_b32_e32 v75, v0
	v_mov_b32_e32 v76, v0
	v_mov_b32_e32 v77, v0
	v_mov_b32_e32 v78, v0
	v_mov_b32_e32 v79, v0
	v_mov_b32_e32 v88, v0
	v_mov_b32_e32 v89, v0
	v_mov_b32_e32 v90, v0
	v_mov_b32_e32 v91, v0
	v_mov_b32_e32 v92, v0
	v_mov_b32_e32 v93, v0
	v_mov_b32_e32 v94, v0
	v_mov_b32_e32 v95, v0
	v_mov_b32_e32 v104, v0
	v_mov_b32_e32 v105, v0
	v_mov_b32_e32 v106, v0
	v_mov_b32_e32 v107, v0
	v_mov_b32_e32 v108, v0
	v_mov_b32_e32 v109, v0
	v_mov_b32_e32 v110, v0
	v_mov_b32_e32 v111, v0
	v_mov_b32_e32 v120, v0
	v_mov_b32_e32 v121, v0
	v_mov_b32_e32 v122, v0
	v_mov_b32_e32 v123, v0
	v_mov_b32_e32 v124, v0
	v_mov_b32_e32 v125, v0
	v_mov_b32_e32 v126, v0
	v_mov_b32_e32 v127, v0
	s_cmp_lt_u32 s3, 4
	s_cbranch_scc0 .Lgsp_0
	s_setprio 1

;     __device__ __forceinline__ bool next(int i, pg8::Unit& u) const { if (c < 128 || i >= 2) return false; const int idx = (c - 128) * 2 + i; u.pm = idx >> 2; u.pn = idx & 3; return true; }
; template <class Epi, class Sched, bool ALIGN_EPI = false, bool SP2 = false, bool F16 = false>
; __device__ __forceinline__ void gemm_phase(PG8_LAS unsigned char* lds, const Gemm g, const Sched& S, const Epi& E, const int wid_in) {
;     ...
;         const bool has_next = S.next(ui + 1, nxt);
;         const char* nA = has_next ? (const char*)g.A + (size_t)nxt.pm * tstep : cA; const char* nB = has_next ? (const char*)g.Bt + (size_t)nxt.pn * tstep : cB;
;     ...
; #pragma unroll
;         for (int a = 0; a < 2; ++a)
; #pragma unroll
;             for (int b = 0; b < 2; ++b)
; #pragma unroll
;                 for (int m = 0; m < 4; ++m)
; #pragma unroll
;                     for (int n = 0; n < 2; ++n) acc[a][b][m][n] = (f32x4){0.f, 0.f, 0.f, 0.f};
;         cur = nxt; cA = nA; cB = nB; ++ui;
.LBB0_507:
	s_ashr_i32 s27, s26, 31
	s_lshl_b64 s[28:29], s[26:27], 19
	s_add_u32 s28, s15, s28
	s_addc_u32 s29, s40, s29
	s_and_b64 s[30:31], s[8:9], exec
	s_cselect_b32 s10, s29, s45
	s_cselect_b32 s27, s28, s44
	s_ashr_i32 s25, s24, 31
	s_lshl_b64 s[30:31], s[24:25], 19
	s_add_u32 s30, s41, s30
	s_addc_u32 s31, s50, s31
	s_and_b64 s[42:43], s[8:9], exec
	s_cselect_b32 s25, s31, s47
	s_cselect_b32 s35, s30, s46
	s_add_u32 s44, s44, 0x40080
	s_addc_u32 s45, s45, 0
	s_add_u32 s37, s46, 0x100
	v_mov_b32_e32 v0, 0
	s_addc_u32 s42, s47, 0
	s_mov_b32 s43, -2
	v_mov_b32_e32 v1, v0
	v_mov_b32_e32 v2, v0
	v_mov_b32_e32 v3, v0
	v_mov_b32_e32 v4, v0
	v_mov_b32_e32 v5, v0
	v_mov_b32_e32 v6, v0
	v_mov_b32_e32 v7, v0
	v_mov_b32_e32 v16, v0
	v_mov_b32_e32 v17, v0
	v_mov_b32_e32 v18, v0
	v_mov_b32_e32 v19, v0
	v_mov_b32_e32 v20, v0
	v_mov_b32_e32 v21, v0
	v_mov_b32_e32 v22, v0
	v_mov_b32_e32 v23, v0
	v_mov_b32_e32 v32, v0
	v_mov_b32_e32 v33, v0
	v_mov_b32_e32 v34, v0
	v_mov_b32_e32 v35, v0
	v_mov_b32_e32 v36, v0
	v_mov_b32_e32 v37, v0
	v_mov_b32_e32 v38, v0
	v_mov_b32_e32 v39, v0
	v_mov_b32_e32 v48, v0
	v_mov_b32_e32 v49, v0
	v_mov_b32_e32 v50, v0
	v_mov_b32_e32 v51, v0
	v_mov_b32_e32 v52, v0
	v_mov_b32_e32 v53, v0
	v_mov_b32_e32 v54, v0
	v_mov_b32_e32 v55, v0
	v_mov_b32_e32 v8, v0
	v_mov_b32_e32 v9, v0
	v_mov_b32_e32 v10, v0
	v_mov_b32_e32 v11, v0
	v_mov_b32_e32 v12, v0
	v_mov_b32_e32 v13, v0
	v_mov_b32_e32 v14, v0
	v_mov_b32_e32 v15, v0
	v_mov_b32_e32 v24, v0
	v_mov_b32_e32 v25, v0
	v_mov_b32_e32 v26, v0
	v_mov_b32_e32 v27, v0
	v_mov_b32_e32 v28, v0
	v_mov_b32_e32 v29, v0
	v_mov_b32_e32 v30, v0
	v_mov_b32_e32 v31, v0
	v_mov_b32_e32 v40, v0
	v_mov_b32_e32 v41, v0
	v_mov_b32_e32 v42, v0
	v_mov_b32_e32 v43, v0
	v_mov_b32_e32 v44, v0
	v_mov_b32_e32 v45, v0
	v_mov_b32_e32 v46, v0
	v_mov_b32_e32 v47, v0
	v_mov_b32_e32 v56, v0
	v_mov_b32_e32 v57, v0
	v_mov_b32_e32 v58, v0
	v_mov_b32_e32 v59, v0
	v_mov_b32_e32 v60, v0
	v_mov_b32_e32 v61, v0
	v_mov_b32_e32 v62, v0
	v_mov_b32_e32 v63, v0
	v_mov_b32_e32 v64, v0
	v_mov_b32_e32 v65, v0
	v_mov_b32_e32 v66, v0
	v_mov_b32_e32 v67, v0
	v_mov_b32_e32 v68, v0
	v_mov_b32_e32 v69, v0
	v_mov_b32_e32 v70, v0
	v_mov_b32_e32 v71, v0
	v_mov_b32_e32 v80, v0
	v_mov_b32_e32 v81, v0
	v_mov_b32_e32 v82, v0
	v_mov_b32_e32 v83, v0
	v_mov_b32_e32 v84, v0
	v_mov_b32_e32 v85, v0
	v_mov_b32_e32 v86, v0
	v_mov_b32_e32 v87, v0
	v_mov_b32_e32 v96, v0
	v_mov_b32_e32 v97, v0
	v_mov_b32_e32 v98, v0
	v_mov_b32_e32 v99, v0
	v_mov_b32_e32 v100, v0
	v_mov_b32_e32 v101, v0
	v_mov_b32_e32 v102, v0
	v_mov_b32_e32 v103, v0
	v_mov_b32_e32 v112, v0
	v_mov_b32_e32 v113, v0
	v_mov_b32_e32 v114, v0
	v_mov_b32_e32 v115, v0
	v_mov_b32_e32 v116, v0
	v_mov_b32_e32 v117, v0
	v_mov_b32_e32 v118, v0
	v_mov_b32_e32 v119, v0
	v_mov_b32_e32 v72, v0
	v_mov_b32_e32 v73, v0
	v_mov_b32_e32 v74, v0
	v_mov_b32_e32 v75, v0
	v_mov_b32_e32 v76, v0
	v_mov_b32_e32 v77, v0
	v_mov_b32_e32 v78, v0
	v_mov_b32_e32 v79, v0
	v_mov_b32_e32 v88, v0
	v_mov_b32_e32 v89, v0
	v_mov_b32_e32 v90, v0
	v_mov_b32_e32 v91, v0
	v_mov_b32_e32 v92, v0
	v_mov_b32_e32 v93, v0
	v_mov_b32_e32 v94, v0
	v_mov_b32_e32 v95, v0
	v_mov_b32_e32 v104, v0
	v_mov_b32_e32 v105, v0
	v_mov_b32_e32 v106, v0
	v_mov_b32_e32 v107, v0
	v_mov_b32_e32 v108, v0
	v_mov_b32_e32 v109, v0
	v_mov_b32_e32 v110, v0
	v_mov_b32_e32 v111, v0
	v_mov_b32_e32 v120, v0
	v_mov_b32_e32 v121, v0
	v_mov_b32_e32 v122, v0
	v_mov_b32_e32 v123, v0
	v_mov_b32_e32 v124, v0
	v_mov_b32_e32 v125, v0
	v_mov_b32_e32 v126, v0
	v_mov_b32_e32 v127, v0
	s_cmp_lt_u32 s3, 4
	s_cbranch_scc0 .Lgsp_1
	s_setprio 1

;     __device__ __forceinline__ bool next(int i, pg8::Unit& u) const { if (c < 128 || i >= 2) return false; const int idx = (c - 128) * 2 + i; u.pm = idx >> 2; u.pn = idx & 3; return true; }
; template <class Epi, class Sched, bool ALIGN_EPI = false, bool SP2 = false, bool F16 = false>
; __device__ __forceinline__ void gemm_phase(PG8_LAS unsigned char* lds, const Gemm g, const Sched& S, const Epi& E, const int wid_in) {
;     ...
;         const bool has_next = S.next(ui + 1, nxt);
;         const char* nA = has_next ? (const char*)g.A + (size_t)nxt.pm * tstep : cA; const char* nB = has_next ? (const char*)g.Bt + (size_t)nxt.pn * tstep : cB;
;     ...
; #pragma unroll
;         for (int a = 0; a < 2; ++a)
; #pragma unroll
;             for (int b = 0; b < 2; ++b)
; #pragma unroll
;                 for (int m = 0; m < 4; ++m)
; #pragma unroll
;                     for (int n = 0; n < 2; ++n) acc[a][b][m][n] = (f32x4){0.f, 0.f, 0.f, 0.f};
;         cur = nxt; cA = nA; cB = nB; ++ui;
.LBB0_584:
	s_ashr_i32 s23, s22, 31
	s_lshl_b64 s[24:25], s[22:23], 19
	s_add_u32 s24, s41, s24
	s_addc_u32 s25, s46, s25
	s_and_b64 s[26:27], s[8:9], exec
	s_cselect_b32 s23, s25, s35
	s_cselect_b32 s31, s24, s34
	s_ashr_i32 s21, s20, 31
	s_lshl_b64 s[26:27], s[20:21], 19
	s_add_u32 s26, s47, s26
	s_addc_u32 s27, s48, s27
	s_and_b64 s[42:43], s[8:9], exec
	s_cselect_b32 s21, s27, s37
	s_cselect_b32 s42, s26, s36
	s_add_u32 s34, s34, 0x40080
	s_addc_u32 s35, s35, 0
	s_add_u32 s43, s36, 0x100
	v_mov_b32_e32 v8, 0
	s_addc_u32 s64, s37, 0
	s_mov_b32 s65, -2
	v_mov_b32_e32 v9, v8
	v_mov_b32_e32 v10, v8
	v_mov_b32_e32 v11, v8
	v_mov_b32_e32 v12, v8
	v_mov_b32_e32 v13, v8
	v_mov_b32_e32 v14, v8
	v_mov_b32_e32 v15, v8
	v_mov_b32_e32 v24, v8
	v_mov_b32_e32 v25, v8
	v_mov_b32_e32 v26, v8
	v_mov_b32_e32 v27, v8
	v_mov_b32_e32 v28, v8
	v_mov_b32_e32 v29, v8
	v_mov_b32_e32 v30, v8
	v_mov_b32_e32 v31, v8
	v_mov_b32_e32 v40, v8
	v_mov_b32_e32 v41, v8
	v_mov_b32_e32 v42, v8
	v_mov_b32_e32 v43, v8
	v_mov_b32_e32 v44, v8
	v_mov_b32_e32 v45, v8
	v_mov_b32_e32 v46, v8
	v_mov_b32_e32 v47, v8
	v_mov_b32_e32 v56, v8
	v_mov_b32_e32 v57, v8
	v_mov_b32_e32 v58, v8
	v_mov_b32_e32 v59, v8
	v_mov_b32_e32 v60, v8
	v_mov_b32_e32 v61, v8
	v_mov_b32_e32 v62, v8
	v_mov_b32_e32 v63, v8
	v_mov_b32_e32 v16, v8
	v_mov_b32_e32 v17, v8
	v_mov_b32_e32 v18, v8
	v_mov_b32_e32 v19, v8
	v_mov_b32_e32 v20, v8
	v_mov_b32_e32 v21, v8
	v_mov_b32_e32 v22, v8
	v_mov_b32_e32 v23, v8
	v_mov_b32_e32 v32, v8
	v_mov_b32_e32 v33, v8
	v_mov_b32_e32 v34, v8
	v_mov_b32_e32 v35, v8
	v_mov_b32_e32 v36, v8
	v_mov_b32_e32 v37, v8
	v_mov_b32_e32 v38, v8
	v_mov_b32_e32 v39, v8
	v_mov_b32_e32 v48, v8
	v_mov_b32_e32 v49, v8
	v_mov_b32_e32 v50, v8
	v_mov_b32_e32 v51, v8
	v_mov_b32_e32 v52, v8
	v_mov_b32_e32 v53, v8
	v_mov_b32_e32 v54, v8
	v_mov_b32_e32 v55, v8
	v_mov_b32_e32 v64, v8
	v_mov_b32_e32 v65, v8
	v_mov_b32_e32 v66, v8
	v_mov_b32_e32 v67, v8
	v_mov_b32_e32 v68, v8
	v_mov_b32_e32 v69, v8
	v_mov_b32_e32 v70, v8
	v_mov_b32_e32 v71, v8
	v_mov_b32_e32 v72, v8
	v_mov_b32_e32 v73, v8
	v_mov_b32_e32 v74, v8
	v_mov_b32_e32 v75, v8
	v_mov_b32_e32 v76, v8
	v_mov_b32_e32 v77, v8
	v_mov_b32_e32 v78, v8
	v_mov_b32_e32 v79, v8
	v_mov_b32_e32 v88, v8
	v_mov_b32_e32 v89, v8
	v_mov_b32_e32 v90, v8
	v_mov_b32_e32 v91, v8
	v_mov_b32_e32 v92, v8
	v_mov_b32_e32 v93, v8
	v_mov_b32_e32 v94, v8
	v_mov_b32_e32 v95, v8
	v_mov_b32_e32 v104, v8
	v_mov_b32_e32 v105, v8
	v_mov_b32_e32 v106, v8
	v_mov_b32_e32 v107, v8
	v_mov_b32_e32 v108, v8
	v_mov_b32_e32 v109, v8
	v_mov_b32_e32 v110, v8
	v_mov_b32_e32 v111, v8
	v_mov_b32_e32 v120, v8
	v_mov_b32_e32 v121, v8
	v_mov_b32_e32 v122, v8
	v_mov_b32_e32 v123, v8
	v_mov_b32_e32 v124, v8
	v_mov_b32_e32 v125, v8
	v_mov_b32_e32 v126, v8
	v_mov_b32_e32 v127, v8
	v_mov_b32_e32 v80, v8
	v_mov_b32_e32 v81, v8
	v_mov_b32_e32 v82, v8
	v_mov_b32_e32 v83, v8
	v_mov_b32_e32 v84, v8
	v_mov_b32_e32 v85, v8
	v_mov_b32_e32 v86, v8
	v_mov_b32_e32 v87, v8
	v_mov_b32_e32 v96, v8
	v_mov_b32_e32 v97, v8
	v_mov_b32_e32 v98, v8
	v_mov_b32_e32 v99, v8
	v_mov_b32_e32 v100, v8
	v_mov_b32_e32 v101, v8
	v_mov_b32_e32 v102, v8
	v_mov_b32_e32 v103, v8
	v_mov_b32_e32 v112, v8
	v_mov_b32_e32 v113, v8
	v_mov_b32_e32 v114, v8
	v_mov_b32_e32 v115, v8
	v_mov_b32_e32 v116, v8
	v_mov_b32_e32 v117, v8
	v_mov_b32_e32 v118, v8
	v_mov_b32_e32 v119, v8
	v_mov_b32_e32 v128, v8
	v_mov_b32_e32 v129, v8
	v_mov_b32_e32 v130, v8
	v_mov_b32_e32 v131, v8
	v_mov_b32_e32 v132, v8
	v_mov_b32_e32 v133, v8
	v_mov_b32_e32 v134, v8
	v_mov_b32_e32 v135, v8
	s_cmp_lt_u32 s3, 4
	s_cbranch_scc0 .Lgsp_2
	s_setprio 1

;     __device__ __forceinline__ bool next(int i, pg8::Unit& u) const { if (c < 128 || i >= 2) return false; const int idx = (c - 128) * 2 + i; u.pm = idx >> 2; u.pn = idx & 3; return true; }
; template <class Epi, class Sched, bool ALIGN_EPI = false, bool SP2 = false, bool F16 = false>
; __device__ __forceinline__ void gemm_phase(PG8_LAS unsigned char* lds, const Gemm g, const Sched& S, const Epi& E, const int wid_in) {
;     ...
;         const bool has_next = S.next(ui + 1, nxt);
;         const char* nA = has_next ? (const char*)g.A + (size_t)nxt.pm * tstep : cA; const char* nB = has_next ? (const char*)g.Bt + (size_t)nxt.pn * tstep : cB;
;         for (int t = 0; t < nt; t += 2) {
.LBB0_618:
	s_mov_b64 s[28:29], 0
	s_cmp_lt_u32 s3, 4
	s_cbranch_scc0 .Lgsp_3
	s_setprio 1

;     __device__ __forceinline__ bool next(int i, pg8::Unit& u) const { if (c < 128 || i >= 2) return false; const int idx = (c - 128) * 2 + i; u.pm = idx >> 2; u.pn = idx & 3; return true; }
; template <class Epi, class Sched, bool ALIGN_EPI = false, bool SP2 = false, bool F16 = false>
; __device__ __forceinline__ void gemm_phase(PG8_LAS unsigned char* lds, const Gemm g, const Sched& S, const Epi& E, const int wid_in) {
;     ...
;         const bool has_next = S.next(ui + 1, nxt);
;         const char* nA = has_next ? (const char*)g.A + (size_t)nxt.pm * tstep : cA; const char* nB = has_next ? (const char*)g.Bt + (size_t)nxt.pn * tstep : cB;
;     ...
; #pragma unroll
;         for (int a = 0; a < 2; ++a)
; #pragma unroll
;             for (int b = 0; b < 2; ++b)
; #pragma unroll
;                 for (int m = 0; m < 4; ++m)
; #pragma unroll
;                     for (int n = 0; n < 2; ++n) acc[a][b][m][n] = (f32x4){0.f, 0.f, 0.f, 0.f};
;         cur = nxt; cA = nA; cB = nB; ++ui;
.LBB0_715:
	s_add_u32 s43, s30, 0x100
	v_mov_b32_e32 v0, 0
	s_addc_u32 s59, s31, 0
	s_mov_b32 s60, -2
	v_mov_b32_e32 v1, v0
	v_mov_b32_e32 v2, v0
	v_mov_b32_e32 v3, v0
	v_mov_b32_e32 v4, v0
	v_mov_b32_e32 v5, v0
	v_mov_b32_e32 v6, v0
	v_mov_b32_e32 v7, v0
	v_mov_b32_e32 v16, v0
	v_mov_b32_e32 v17, v0
	v_mov_b32_e32 v18, v0
	v_mov_b32_e32 v19, v0
	v_mov_b32_e32 v20, v0
	v_mov_b32_e32 v21, v0
	v_mov_b32_e32 v22, v0
	v_mov_b32_e32 v23, v0
	v_mov_b32_e32 v32, v0
	v_mov_b32_e32 v33, v0
	v_mov_b32_e32 v34, v0
	v_mov_b32_e32 v35, v0
	v_mov_b32_e32 v36, v0
	v_mov_b32_e32 v37, v0
	v_mov_b32_e32 v38, v0
	v_mov_b32_e32 v39, v0
	v_mov_b32_e32 v48, v0
	v_mov_b32_e32 v49, v0
	v_mov_b32_e32 v50, v0
	v_mov_b32_e32 v51, v0
	v_mov_b32_e32 v52, v0
	v_mov_b32_e32 v53, v0
	v_mov_b32_e32 v54, v0
	v_mov_b32_e32 v55, v0
	v_mov_b32_e32 v8, v0
	v_mov_b32_e32 v9, v0
	v_mov_b32_e32 v10, v0
	v_mov_b32_e32 v11, v0
	v_mov_b32_e32 v12, v0
	v_mov_b32_e32 v13, v0
	v_mov_b32_e32 v14, v0
	v_mov_b32_e32 v15, v0
	v_mov_b32_e32 v24, v0
	v_mov_b32_e32 v25, v0
	v_mov_b32_e32 v26, v0
	v_mov_b32_e32 v27, v0
	v_mov_b32_e32 v28, v0
	v_mov_b32_e32 v29, v0
	v_mov_b32_e32 v30, v0
	v_mov_b32_e32 v31, v0
	v_mov_b32_e32 v40, v0
	v_mov_b32_e32 v41, v0
	v_mov_b32_e32 v42, v0
	v_mov_b32_e32 v43, v0
	v_mov_b32_e32 v44, v0
	v_mov_b32_e32 v45, v0
	v_mov_b32_e32 v46, v0
	v_mov_b32_e32 v47, v0
	v_mov_b32_e32 v56, v0
	v_mov_b32_e32 v57, v0
	v_mov_b32_e32 v58, v0
	v_mov_b32_e32 v59, v0
	v_mov_b32_e32 v60, v0
	v_mov_b32_e32 v61, v0
	v_mov_b32_e32 v62, v0
	v_mov_b32_e32 v63, v0
	v_mov_b32_e32 v64, v0
	v_mov_b32_e32 v65, v0
	v_mov_b32_e32 v66, v0
	v_mov_b32_e32 v67, v0
	v_mov_b32_e32 v68, v0
	v_mov_b32_e32 v69, v0
	v_mov_b32_e32 v70, v0
	v_mov_b32_e32 v71, v0
	v_mov_b32_e32 v80, v0
	v_mov_b32_e32 v81, v0
	v_mov_b32_e32 v82, v0
	v_mov_b32_e32 v83, v0
	v_mov_b32_e32 v84, v0
	v_mov_b32_e32 v85, v0
	v_mov_b32_e32 v86, v0
	v_mov_b32_e32 v87, v0
	v_mov_b32_e32 v96, v0
	v_mov_b32_e32 v97, v0
	v_mov_b32_e32 v98, v0
	v_mov_b32_e32 v99, v0
	v_mov_b32_e32 v100, v0
	v_mov_b32_e32 v101, v0
	v_mov_b32_e32 v102, v0
	v_mov_b32_e32 v103, v0
	v_mov_b32_e32 v112, v0
	v_mov_b32_e32 v113, v0
	v_mov_b32_e32 v114, v0
	v_mov_b32_e32 v115, v0
	v_mov_b32_e32 v116, v0
	v_mov_b32_e32 v117, v0
	v_mov_b32_e32 v118, v0
	v_mov_b32_e32 v119, v0
	v_mov_b32_e32 v72, v0
	v_mov_b32_e32 v73, v0
	v_mov_b32_e32 v74, v0
	v_mov_b32_e32 v75, v0
	v_mov_b32_e32 v76, v0
	v_mov_b32_e32 v77, v0
	v_mov_b32_e32 v78, v0
	v_mov_b32_e32 v79, v0
	v_mov_b32_e32 v88, v0
	v_mov_b32_e32 v89, v0
	v_mov_b32_e32 v90, v0
	v_mov_b32_e32 v91, v0
	v_mov_b32_e32 v92, v0
	v_mov_b32_e32 v93, v0
	v_mov_b32_e32 v94, v0
	v_mov_b32_e32 v95, v0
	v_mov_b32_e32 v104, v0
	v_mov_b32_e32 v105, v0
	v_mov_b32_e32 v106, v0
	v_mov_b32_e32 v107, v0
	v_mov_b32_e32 v108, v0
	v_mov_b32_e32 v109, v0
	v_mov_b32_e32 v110, v0
	v_mov_b32_e32 v111, v0
	v_mov_b32_e32 v120, v0
	v_mov_b32_e32 v121, v0
	v_mov_b32_e32 v122, v0
	v_mov_b32_e32 v123, v0
	v_mov_b32_e32 v124, v0
	v_mov_b32_e32 v125, v0
	v_mov_b32_e32 v126, v0
	v_mov_b32_e32 v127, v0
	s_cmp_lt_u32 s3, 4
	s_cbranch_scc0 .Lgsp_4
	s_setprio 1

;     __device__ __forceinline__ bool next(int i, pg8::Unit& u) const { if (c < 128 || i >= 2) return false; const int idx = (c - 128) * 2 + i; u.pm = idx >> 2; u.pn = idx & 3; return true; }
; template <class Epi, class Sched, bool ALIGN_EPI = false, bool SP2 = false, bool F16 = false>
; __device__ __forceinline__ void gemm_phase(PG8_LAS unsigned char* lds, const Gemm g, const Sched& S, const Epi& E, const int wid_in) {
;     ...
;         const bool has_next = S.next(ui + 1, nxt);
;         const char* nA = has_next ? (const char*)g.A + (size_t)nxt.pm * tstep : cA; const char* nB = has_next ? (const char*)g.Bt + (size_t)nxt.pn * tstep : cB;
;     ...
; #pragma unroll
;         for (int a = 0; a < 2; ++a)
; #pragma unroll
;             for (int b = 0; b < 2; ++b)
; #pragma unroll
;                 for (int m = 0; m < 4; ++m)
; #pragma unroll
;                     for (int n = 0; n < 2; ++n) acc[a][b][m][n] = (f32x4){0.f, 0.f, 0.f, 0.f};
;         cur = nxt; cA = nA; cB = nB; ++ui;
.LBB0_811:
	s_ashr_i32 s31, s30, 31
	s_lshl_b64 s[14:15], s[30:31], 19
	s_add_u32 s34, s10, s14
	s_addc_u32 s35, s11, s15
	s_and_b64 s[14:15], s[8:9], exec
	s_cselect_b32 s14, s35, s47
	s_cselect_b32 s15, s34, s46
	s_ashr_i32 s29, s28, 31
	s_lshl_b64 s[36:37], s[28:29], 19
	s_add_u32 s36, s53, s36
	s_addc_u32 s37, s54, s37
	s_and_b64 s[40:41], s[8:9], exec
	s_cselect_b32 s29, s37, s49
	s_cselect_b32 s31, s36, s48
	s_add_u32 s46, s46, 0x40080
	s_addc_u32 s47, s47, 0
	s_add_u32 s40, s48, 0x100
	v_mov_b32_e32 v0, 0
	s_addc_u32 s41, s49, 0
	s_mov_b32 s42, -2
	v_mov_b32_e32 v1, v0
	v_mov_b32_e32 v2, v0
	v_mov_b32_e32 v3, v0
	v_mov_b32_e32 v4, v0
	v_mov_b32_e32 v5, v0
	v_mov_b32_e32 v6, v0
	v_mov_b32_e32 v7, v0
	v_mov_b32_e32 v16, v0
	v_mov_b32_e32 v17, v0
	v_mov_b32_e32 v18, v0
	v_mov_b32_e32 v19, v0
	v_mov_b32_e32 v20, v0
	v_mov_b32_e32 v21, v0
	v_mov_b32_e32 v22, v0
	v_mov_b32_e32 v23, v0
	v_mov_b32_e32 v32, v0
	v_mov_b32_e32 v33, v0
	v_mov_b32_e32 v34, v0
	v_mov_b32_e32 v35, v0
	v_mov_b32_e32 v36, v0
	v_mov_b32_e32 v37, v0
	v_mov_b32_e32 v38, v0
	v_mov_b32_e32 v39, v0
	v_mov_b32_e32 v48, v0
	v_mov_b32_e32 v49, v0
	v_mov_b32_e32 v50, v0
	v_mov_b32_e32 v51, v0
	v_mov_b32_e32 v52, v0
	v_mov_b32_e32 v53, v0
	v_mov_b32_e32 v54, v0
	v_mov_b32_e32 v55, v0
	v_mov_b32_e32 v8, v0
	v_mov_b32_e32 v9, v0
	v_mov_b32_e32 v10, v0
	v_mov_b32_e32 v11, v0
	v_mov_b32_e32 v12, v0
	v_mov_b32_e32 v13, v0
	v_mov_b32_e32 v14, v0
	v_mov_b32_e32 v15, v0
	v_mov_b32_e32 v24, v0
	v_mov_b32_e32 v25, v0
	v_mov_b32_e32 v26, v0
	v_mov_b32_e32 v27, v0
	v_mov_b32_e32 v28, v0
	v_mov_b32_e32 v29, v0
	v_mov_b32_e32 v30, v0
	v_mov_b32_e32 v31, v0
	v_mov_b32_e32 v40, v0
	v_mov_b32_e32 v41, v0
	v_mov_b32_e32 v42, v0
	v_mov_b32_e32 v43, v0
	v_mov_b32_e32 v44, v0
	v_mov_b32_e32 v45, v0
	v_mov_b32_e32 v46, v0
	v_mov_b32_e32 v47, v0
	v_mov_b32_e32 v56, v0
	v_mov_b32_e32 v57, v0
	v_mov_b32_e32 v58, v0
	v_mov_b32_e32 v59, v0
	v_mov_b32_e32 v60, v0
	v_mov_b32_e32 v61, v0
	v_mov_b32_e32 v62, v0
	v_mov_b32_e32 v63, v0
	v_mov_b32_e32 v64, v0
	v_mov_b32_e32 v65, v0
	v_mov_b32_e32 v66, v0
	v_mov_b32_e32 v67, v0
	v_mov_b32_e32 v68, v0
	v_mov_b32_e32 v69, v0
	v_mov_b32_e32 v70, v0
	v_mov_b32_e32 v71, v0
	v_mov_b32_e32 v80, v0
	v_mov_b32_e32 v81, v0
	v_mov_b32_e32 v82, v0
	v_mov_b32_e32 v83, v0
	v_mov_b32_e32 v84, v0
	v_mov_b32_e32 v85, v0
	v_mov_b32_e32 v86, v0
	v_mov_b32_e32 v87, v0
	v_mov_b32_e32 v96, v0
	v_mov_b32_e32 v97, v0
	v_mov_b32_e32 v98, v0
	v_mov_b32_e32 v99, v0
	v_mov_b32_e32 v100, v0
	v_mov_b32_e32 v101, v0
	v_mov_b32_e32 v102, v0
	v_mov_b32_e32 v103, v0
	v_mov_b32_e32 v120, v0
	v_mov_b32_e32 v121, v0
	v_mov_b32_e32 v122, v0
	v_mov_b32_e32 v123, v0
	v_mov_b32_e32 v124, v0
	v_mov_b32_e32 v125, v0
	v_mov_b32_e32 v126, v0
	v_mov_b32_e32 v127, v0
	v_mov_b32_e32 v72, v0
	v_mov_b32_e32 v73, v0
	v_mov_b32_e32 v74, v0
	v_mov_b32_e32 v75, v0
	v_mov_b32_e32 v76, v0
	v_mov_b32_e32 v77, v0
	v_mov_b32_e32 v78, v0
	v_mov_b32_e32 v79, v0
	v_mov_b32_e32 v88, v0
	v_mov_b32_e32 v89, v0
	v_mov_b32_e32 v90, v0
	v_mov_b32_e32 v91, v0
	v_mov_b32_e32 v92, v0
	v_mov_b32_e32 v93, v0
	v_mov_b32_e32 v94, v0
	v_mov_b32_e32 v95, v0
	v_mov_b32_e32 v104, v0
	v_mov_b32_e32 v105, v0
	v_mov_b32_e32 v106, v0
	v_mov_b32_e32 v107, v0
	v_mov_b32_e32 v108, v0
	v_mov_b32_e32 v109, v0
	v_mov_b32_e32 v110, v0
	v_mov_b32_e32 v111, v0
	v_mov_b32_e32 v136, v0
	v_mov_b32_e32 v137, v0
	v_mov_b32_e32 v138, v0
	v_mov_b32_e32 v139, v0
	v_mov_b32_e32 v140, v0
	v_mov_b32_e32 v141, v0
	v_mov_b32_e32 v142, v0
	v_mov_b32_e32 v143, v0
	s_cmp_lt_u32 s3, 4
	s_cbranch_scc0 .Lgsp_5
	s_setprio 1

;     __device__ __forceinline__ bool next(int i, pg8::Unit& u) const { if (c < 128 || i >= 2) return false; const int idx = (c - 128) * 2 + i; u.pm = idx >> 2; u.pn = idx & 3; return true; }
; template <class Epi, class Sched, bool ALIGN_EPI = false, bool SP2 = false, bool F16 = false>
; __device__ __forceinline__ void gemm_phase(PG8_LAS unsigned char* lds, const Gemm g, const Sched& S, const Epi& E, const int wid_in) {
;     ...
;         const bool has_next = S.next(ui + 1, nxt);
;         const char* nA = has_next ? (const char*)g.A + (size_t)nxt.pm * tstep : cA; const char* nB = has_next ? (const char*)g.Bt + (size_t)nxt.pn * tstep : cB;
;     ...
; #pragma unroll
;         for (int a = 0; a < 2; ++a)
; #pragma unroll
;             for (int b = 0; b < 2; ++b)
; #pragma unroll
;                 for (int m = 0; m < 4; ++m)
; #pragma unroll
;                     for (int n = 0; n < 2; ++n) acc[a][b][m][n] = (f32x4){0.f, 0.f, 0.f, 0.f};
;         cur = nxt; cA = nA; cB = nB; ++ui;
.LBB0_901:
	s_ashr_i32 s35, s34, 31
	s_lshl_b64 s[36:37], s[34:35], 19
	s_add_u32 s36, s61, s36
	s_addc_u32 s37, s62, s37
	s_and_b64 s[42:43], s[8:9], exec
	s_cselect_b32 s11, s37, s47
	s_cselect_b32 s13, s36, s46
	s_ashr_i32 s31, s30, 31
	s_lshl_b64 s[42:43], s[30:31], 19
	s_add_u32 s44, s63, s42
	s_addc_u32 s45, s64, s43
	s_and_b64 s[42:43], s[8:9], exec
	s_cselect_b32 s31, s45, s49
	s_cselect_b32 s35, s44, s48
	s_add_u32 s46, s46, 0x40080
	s_addc_u32 s47, s47, 0
	s_add_u32 s42, s48, 0x100
	v_mov_b32_e32 v0, 0
	s_addc_u32 s43, s49, 0
	s_mov_b32 s52, -2
	s_waitcnt lgkmcnt(0)
	v_mov_b32_e32 v1, v0
	v_mov_b32_e32 v2, v0
	v_mov_b32_e32 v3, v0
	v_mov_b32_e32 v4, v0
	v_mov_b32_e32 v5, v0
	v_mov_b32_e32 v6, v0
	v_mov_b32_e32 v7, v0
	v_mov_b32_e32 v16, v0
	v_mov_b32_e32 v17, v0
	v_mov_b32_e32 v18, v0
	v_mov_b32_e32 v19, v0
	v_mov_b32_e32 v20, v0
	v_mov_b32_e32 v21, v0
	v_mov_b32_e32 v22, v0
	v_mov_b32_e32 v23, v0
	v_mov_b32_e32 v32, v0
	v_mov_b32_e32 v33, v0
	v_mov_b32_e32 v34, v0
	v_mov_b32_e32 v35, v0
	v_mov_b32_e32 v36, v0
	v_mov_b32_e32 v37, v0
	v_mov_b32_e32 v38, v0
	v_mov_b32_e32 v39, v0
	v_mov_b32_e32 v48, v0
	v_mov_b32_e32 v49, v0
	v_mov_b32_e32 v50, v0
	v_mov_b32_e32 v51, v0
	v_mov_b32_e32 v52, v0
	v_mov_b32_e32 v53, v0
	v_mov_b32_e32 v54, v0
	v_mov_b32_e32 v55, v0
	v_mov_b32_e32 v8, v0
	v_mov_b32_e32 v9, v0
	v_mov_b32_e32 v10, v0
	v_mov_b32_e32 v11, v0
	v_mov_b32_e32 v12, v0
	v_mov_b32_e32 v13, v0
	v_mov_b32_e32 v14, v0
	v_mov_b32_e32 v15, v0
	v_mov_b32_e32 v24, v0
	v_mov_b32_e32 v25, v0
	v_mov_b32_e32 v26, v0
	v_mov_b32_e32 v27, v0
	v_mov_b32_e32 v28, v0
	v_mov_b32_e32 v29, v0
	v_mov_b32_e32 v30, v0
	v_mov_b32_e32 v31, v0
	v_mov_b32_e32 v40, v0
	v_mov_b32_e32 v41, v0
	v_mov_b32_e32 v42, v0
	v_mov_b32_e32 v43, v0
	v_mov_b32_e32 v44, v0
	v_mov_b32_e32 v45, v0
	v_mov_b32_e32 v46, v0
	v_mov_b32_e32 v47, v0
	v_mov_b32_e32 v56, v0
	v_mov_b32_e32 v57, v0
	v_mov_b32_e32 v58, v0
	v_mov_b32_e32 v59, v0
	v_mov_b32_e32 v60, v0
	v_mov_b32_e32 v61, v0
	v_mov_b32_e32 v62, v0
	v_mov_b32_e32 v63, v0
	v_mov_b32_e32 v64, v0
	v_mov_b32_e32 v65, v0
	v_mov_b32_e32 v66, v0
	v_mov_b32_e32 v67, v0
	v_mov_b32_e32 v68, v0
	v_mov_b32_e32 v69, v0
	v_mov_b32_e32 v70, v0
	v_mov_b32_e32 v71, v0
	v_mov_b32_e32 v80, v0
	v_mov_b32_e32 v81, v0
	v_mov_b32_e32 v82, v0
	v_mov_b32_e32 v83, v0
	v_mov_b32_e32 v84, v0
	v_mov_b32_e32 v85, v0
	v_mov_b32_e32 v86, v0
	v_mov_b32_e32 v87, v0
	v_mov_b32_e32 v96, v0
	v_mov_b32_e32 v97, v0
	v_mov_b32_e32 v98, v0
	v_mov_b32_e32 v99, v0
	v_mov_b32_e32 v100, v0
	v_mov_b32_e32 v101, v0
	v_mov_b32_e32 v102, v0
	v_mov_b32_e32 v103, v0
	v_mov_b32_e32 v112, v0
	v_mov_b32_e32 v113, v0
	v_mov_b32_e32 v114, v0
	v_mov_b32_e32 v115, v0
	v_mov_b32_e32 v116, v0
	v_mov_b32_e32 v117, v0
	v_mov_b32_e32 v118, v0
	v_mov_b32_e32 v119, v0
	v_mov_b32_e32 v72, v0
	v_mov_b32_e32 v73, v0
	v_mov_b32_e32 v74, v0
	v_mov_b32_e32 v75, v0
	v_mov_b32_e32 v76, v0
	v_mov_b32_e32 v77, v0
	v_mov_b32_e32 v78, v0
	v_mov_b32_e32 v79, v0
	v_mov_b32_e32 v88, v0
	v_mov_b32_e32 v89, v0
	v_mov_b32_e32 v90, v0
	v_mov_b32_e32 v91, v0
	v_mov_b32_e32 v92, v0
	v_mov_b32_e32 v93, v0
	v_mov_b32_e32 v94, v0
	v_mov_b32_e32 v95, v0
	v_mov_b32_e32 v104, v0
	v_mov_b32_e32 v105, v0
	v_mov_b32_e32 v106, v0
	v_mov_b32_e32 v107, v0
	v_mov_b32_e32 v108, v0
	v_mov_b32_e32 v109, v0
	v_mov_b32_e32 v110, v0
	v_mov_b32_e32 v111, v0
	v_mov_b32_e32 v120, v0
	v_mov_b32_e32 v121, v0
	v_mov_b32_e32 v122, v0
	v_mov_b32_e32 v123, v0
	v_mov_b32_e32 v124, v0
	v_mov_b32_e32 v125, v0
	v_mov_b32_e32 v126, v0
	v_mov_b32_e32 v127, v0
	s_cmp_lt_u32 s3, 4
	s_cbranch_scc0 .Lgsp_6
	s_setprio 1

;     __device__ __forceinline__ bool next(int i, pg8::Unit& u) const { if (c < 128 || i >= 2) return false; const int idx = (c - 128) * 2 + i; u.pm = idx >> 2; u.pn = idx & 3; return true; }
; template <class Epi, class Sched, bool ALIGN_EPI = false, bool SP2 = false, bool F16 = false>
; __device__ __forceinline__ void gemm_phase(PG8_LAS unsigned char* lds, const Gemm g, const Sched& S, const Epi& E, const int wid_in) {
;     ...
;         const bool has_next = S.next(ui + 1, nxt);
;         const char* nA = has_next ? (const char*)g.A + (size_t)nxt.pm * tstep : cA; const char* nB = has_next ? (const char*)g.Bt + (size_t)nxt.pn * tstep : cB;
;     ...
; #pragma unroll
;         for (int a = 0; a < 2; ++a)
; #pragma unroll
;             for (int b = 0; b < 2; ++b)
; #pragma unroll
;                 for (int m = 0; m < 4; ++m)
; #pragma unroll
;                     for (int n = 0; n < 2; ++n) acc[a][b][m][n] = (f32x4){0.f, 0.f, 0.f, 0.f};
;         cur = nxt; cA = nA; cB = nB; ++ui;
.LBB0_1164:
	s_ashr_i32 s35, s34, 31
	s_lshl_b64 s[36:37], s[34:35], 19
	s_add_u32 s36, s15, s36
	s_addc_u32 s37, s19, s37
	s_and_b64 s[42:43], s[10:11], exec
	s_cselect_b32 s35, s37, s49
	s_cselect_b32 s42, s36, s48
	s_ashr_i32 s31, s30, 31
	s_lshl_b64 s[44:45], s[30:31], 19
	s_add_u32 s44, s21, s44
	s_addc_u32 s45, s40, s45
	s_and_b64 s[52:53], s[10:11], exec
	s_cselect_b32 s31, s45, s51
	s_cselect_b32 s43, s44, s50
	s_add_u32 s48, s48, 0x40080
	s_addc_u32 s49, s49, 0
	s_add_u32 s47, s50, 0x100
	v_mov_b32_e32 v0, 0
	s_addc_u32 s63, s51, 0
	s_mov_b32 s64, -2
	v_mov_b32_e32 v1, v0
	v_mov_b32_e32 v2, v0
	v_mov_b32_e32 v3, v0
	v_mov_b32_e32 v4, v0
	v_mov_b32_e32 v5, v0
	v_mov_b32_e32 v6, v0
	v_mov_b32_e32 v7, v0
	v_mov_b32_e32 v16, v0
	v_mov_b32_e32 v17, v0
	v_mov_b32_e32 v18, v0
	v_mov_b32_e32 v19, v0
	v_mov_b32_e32 v20, v0
	v_mov_b32_e32 v21, v0
	v_mov_b32_e32 v22, v0
	v_mov_b32_e32 v23, v0
	v_mov_b32_e32 v32, v0
	v_mov_b32_e32 v33, v0
	v_mov_b32_e32 v34, v0
	v_mov_b32_e32 v35, v0
	v_mov_b32_e32 v36, v0
	v_mov_b32_e32 v37, v0
	v_mov_b32_e32 v38, v0
	v_mov_b32_e32 v39, v0
	v_mov_b32_e32 v48, v0
	v_mov_b32_e32 v49, v0
	v_mov_b32_e32 v50, v0
	v_mov_b32_e32 v51, v0
	v_mov_b32_e32 v52, v0
	v_mov_b32_e32 v53, v0
	v_mov_b32_e32 v54, v0
	v_mov_b32_e32 v55, v0
	v_mov_b32_e32 v8, v0
	v_mov_b32_e32 v9, v0
	v_mov_b32_e32 v10, v0
	v_mov_b32_e32 v11, v0
	v_mov_b32_e32 v12, v0
	v_mov_b32_e32 v13, v0
	v_mov_b32_e32 v14, v0
	v_mov_b32_e32 v15, v0
	v_mov_b32_e32 v24, v0
	v_mov_b32_e32 v25, v0
	v_mov_b32_e32 v26, v0
	v_mov_b32_e32 v27, v0
	v_mov_b32_e32 v28, v0
	v_mov_b32_e32 v29, v0
	v_mov_b32_e32 v30, v0
	v_mov_b32_e32 v31, v0
	v_mov_b32_e32 v40, v0
	v_mov_b32_e32 v41, v0
	v_mov_b32_e32 v42, v0
	v_mov_b32_e32 v43, v0
	v_mov_b32_e32 v44, v0
	v_mov_b32_e32 v45, v0
	v_mov_b32_e32 v46, v0
	v_mov_b32_e32 v47, v0
	v_mov_b32_e32 v56, v0
	v_mov_b32_e32 v57, v0
	v_mov_b32_e32 v58, v0
	v_mov_b32_e32 v59, v0
	v_mov_b32_e32 v60, v0
	v_mov_b32_e32 v61, v0
	v_mov_b32_e32 v62, v0
	v_mov_b32_e32 v63, v0
	v_mov_b32_e32 v64, v0
	v_mov_b32_e32 v65, v0
	v_mov_b32_e32 v66, v0
	v_mov_b32_e32 v67, v0
	v_mov_b32_e32 v68, v0
	v_mov_b32_e32 v69, v0
	v_mov_b32_e32 v70, v0
	v_mov_b32_e32 v71, v0
	v_mov_b32_e32 v80, v0
	v_mov_b32_e32 v81, v0
	v_mov_b32_e32 v82, v0
	v_mov_b32_e32 v83, v0
	v_mov_b32_e32 v84, v0
	v_mov_b32_e32 v85, v0
	v_mov_b32_e32 v86, v0
	v_mov_b32_e32 v87, v0
	v_mov_b32_e32 v96, v0
	v_mov_b32_e32 v97, v0
	v_mov_b32_e32 v98, v0
	v_mov_b32_e32 v99, v0
	v_mov_b32_e32 v100, v0
	v_mov_b32_e32 v101, v0
	v_mov_b32_e32 v102, v0
	v_mov_b32_e32 v103, v0
	v_mov_b32_e32 v112, v0
	v_mov_b32_e32 v113, v0
	v_mov_b32_e32 v114, v0
	v_mov_b32_e32 v115, v0
	v_mov_b32_e32 v116, v0
	v_mov_b32_e32 v117, v0
	v_mov_b32_e32 v118, v0
	v_mov_b32_e32 v119, v0
	v_mov_b32_e32 v72, v0
	v_mov_b32_e32 v73, v0
	v_mov_b32_e32 v74, v0
	v_mov_b32_e32 v75, v0
	v_mov_b32_e32 v76, v0
	v_mov_b32_e32 v77, v0
	v_mov_b32_e32 v78, v0
	v_mov_b32_e32 v79, v0
	v_mov_b32_e32 v88, v0
	v_mov_b32_e32 v89, v0
	v_mov_b32_e32 v90, v0
	v_mov_b32_e32 v91, v0
	v_mov_b32_e32 v92, v0
	v_mov_b32_e32 v93, v0
	v_mov_b32_e32 v94, v0
	v_mov_b32_e32 v95, v0
	v_mov_b32_e32 v104, v0
	v_mov_b32_e32 v105, v0
	v_mov_b32_e32 v106, v0
	v_mov_b32_e32 v107, v0
	v_mov_b32_e32 v108, v0
	v_mov_b32_e32 v109, v0
	v_mov_b32_e32 v110, v0
	v_mov_b32_e32 v111, v0
	v_mov_b32_e32 v120, v0
	v_mov_b32_e32 v121, v0
	v_mov_b32_e32 v122, v0
	v_mov_b32_e32 v123, v0
	v_mov_b32_e32 v124, v0
	v_mov_b32_e32 v125, v0
	v_mov_b32_e32 v126, v0
	v_mov_b32_e32 v127, v0
	s_cmp_lt_u32 s3, 4
	s_cbranch_scc0 .Lgsp_7
	s_setprio 1

;     __device__ __forceinline__ bool next(int i, pg8::Unit& u) const { if (c < 128 || i >= 2) return false; const int idx = (c - 128) * 2 + i; u.pm = idx >> 2; u.pn = idx & 3; return true; }
; template <class Epi, class Sched, bool ALIGN_EPI = false, bool SP2 = false, bool F16 = false>
; __device__ __forceinline__ void gemm_phase(PG8_LAS unsigned char* lds, const Gemm g, const Sched& S, const Epi& E, const int wid_in) {
;     ...
;         const bool has_next = S.next(ui + 1, nxt);
;         const char* nA = has_next ? (const char*)g.A + (size_t)nxt.pm * tstep : cA; const char* nB = has_next ? (const char*)g.Bt + (size_t)nxt.pn * tstep : cB;
;     ...
; #pragma unroll
;         for (int a = 0; a < 2; ++a)
; #pragma unroll
;             for (int b = 0; b < 2; ++b)
; #pragma unroll
;                 for (int m = 0; m < 4; ++m)
; #pragma unroll
;                     for (int n = 0; n < 2; ++n) acc[a][b][m][n] = (f32x4){0.f, 0.f, 0.f, 0.f};
;         cur = nxt; cA = nA; cB = nB; ++ui;
.LBB0_1241:
	s_ashr_i32 s29, s28, 31
	s_lshl_b64 s[30:31], s[28:29], 19
	s_add_u32 s30, s21, s30
	s_addc_u32 s31, s40, s31
	s_and_b64 s[34:35], s[10:11], exec
	s_cselect_b32 s29, s31, s47
	s_cselect_b32 s42, s30, s46
	s_ashr_i32 s27, s26, 31
	s_lshl_b64 s[34:35], s[26:27], 19
	s_add_u32 s34, s41, s34
	s_addc_u32 s35, s52, s35
	s_and_b64 s[50:51], s[10:11], exec
	s_cselect_b32 s27, s35, s49
	s_cselect_b32 s43, s34, s48
	s_add_u32 s46, s46, 0x40080
	s_addc_u32 s47, s47, 0
	s_add_u32 s45, s48, 0x100
	v_mov_b32_e32 v8, 0
	s_addc_u32 s66, s49, 0
	s_mov_b32 s67, -2
	v_mov_b32_e32 v9, v8
	v_mov_b32_e32 v10, v8
	v_mov_b32_e32 v11, v8
	v_mov_b32_e32 v12, v8
	v_mov_b32_e32 v13, v8
	v_mov_b32_e32 v14, v8
	v_mov_b32_e32 v15, v8
	v_mov_b32_e32 v24, v8
	v_mov_b32_e32 v25, v8
	v_mov_b32_e32 v26, v8
	v_mov_b32_e32 v27, v8
	v_mov_b32_e32 v28, v8
	v_mov_b32_e32 v29, v8
	v_mov_b32_e32 v30, v8
	v_mov_b32_e32 v31, v8
	v_mov_b32_e32 v40, v8
	v_mov_b32_e32 v41, v8
	v_mov_b32_e32 v42, v8
	v_mov_b32_e32 v43, v8
	v_mov_b32_e32 v44, v8
	v_mov_b32_e32 v45, v8
	v_mov_b32_e32 v46, v8
	v_mov_b32_e32 v47, v8
	v_mov_b32_e32 v56, v8
	v_mov_b32_e32 v57, v8
	v_mov_b32_e32 v58, v8
	v_mov_b32_e32 v59, v8
	v_mov_b32_e32 v60, v8
	v_mov_b32_e32 v61, v8
	v_mov_b32_e32 v62, v8
	v_mov_b32_e32 v63, v8
	v_mov_b32_e32 v16, v8
	v_mov_b32_e32 v17, v8
	v_mov_b32_e32 v18, v8
	v_mov_b32_e32 v19, v8
	v_mov_b32_e32 v20, v8
	v_mov_b32_e32 v21, v8
	v_mov_b32_e32 v22, v8
	v_mov_b32_e32 v23, v8
	v_mov_b32_e32 v32, v8
	v_mov_b32_e32 v33, v8
	v_mov_b32_e32 v34, v8
	v_mov_b32_e32 v35, v8
	v_mov_b32_e32 v36, v8
	v_mov_b32_e32 v37, v8
	v_mov_b32_e32 v38, v8
	v_mov_b32_e32 v39, v8
	v_mov_b32_e32 v48, v8
	v_mov_b32_e32 v49, v8
	v_mov_b32_e32 v50, v8
	v_mov_b32_e32 v51, v8
	v_mov_b32_e32 v52, v8
	v_mov_b32_e32 v53, v8
	v_mov_b32_e32 v54, v8
	v_mov_b32_e32 v55, v8
	v_mov_b32_e32 v64, v8
	v_mov_b32_e32 v65, v8
	v_mov_b32_e32 v66, v8
	v_mov_b32_e32 v67, v8
	v_mov_b32_e32 v68, v8
	v_mov_b32_e32 v69, v8
	v_mov_b32_e32 v70, v8
	v_mov_b32_e32 v71, v8
	v_mov_b32_e32 v72, v8
	v_mov_b32_e32 v73, v8
	v_mov_b32_e32 v74, v8
	v_mov_b32_e32 v75, v8
	v_mov_b32_e32 v76, v8
	v_mov_b32_e32 v77, v8
	v_mov_b32_e32 v78, v8
	v_mov_b32_e32 v79, v8
	v_mov_b32_e32 v88, v8
	v_mov_b32_e32 v89, v8
	v_mov_b32_e32 v90, v8
	v_mov_b32_e32 v91, v8
	v_mov_b32_e32 v92, v8
	v_mov_b32_e32 v93, v8
	v_mov_b32_e32 v94, v8
	v_mov_b32_e32 v95, v8
	v_mov_b32_e32 v104, v8
	v_mov_b32_e32 v105, v8
	v_mov_b32_e32 v106, v8
	v_mov_b32_e32 v107, v8
	v_mov_b32_e32 v108, v8
	v_mov_b32_e32 v109, v8
	v_mov_b32_e32 v110, v8
	v_mov_b32_e32 v111, v8
	v_mov_b32_e32 v120, v8
	v_mov_b32_e32 v121, v8
	v_mov_b32_e32 v122, v8
	v_mov_b32_e32 v123, v8
	v_mov_b32_e32 v124, v8
	v_mov_b32_e32 v125, v8
	v_mov_b32_e32 v126, v8
	v_mov_b32_e32 v127, v8
	v_mov_b32_e32 v80, v8
	v_mov_b32_e32 v81, v8
	v_mov_b32_e32 v82, v8
	v_mov_b32_e32 v83, v8
	v_mov_b32_e32 v84, v8
	v_mov_b32_e32 v85, v8
	v_mov_b32_e32 v86, v8
	v_mov_b32_e32 v87, v8
	v_mov_b32_e32 v96, v8
	v_mov_b32_e32 v97, v8
	v_mov_b32_e32 v98, v8
	v_mov_b32_e32 v99, v8
	v_mov_b32_e32 v100, v8
	v_mov_b32_e32 v101, v8
	v_mov_b32_e32 v102, v8
	v_mov_b32_e32 v103, v8
	v_mov_b32_e32 v112, v8
	v_mov_b32_e32 v113, v8
	v_mov_b32_e32 v114, v8
	v_mov_b32_e32 v115, v8
	v_mov_b32_e32 v116, v8
	v_mov_b32_e32 v117, v8
	v_mov_b32_e32 v118, v8
	v_mov_b32_e32 v119, v8
	v_mov_b32_e32 v128, v8
	v_mov_b32_e32 v129, v8
	v_mov_b32_e32 v130, v8
	v_mov_b32_e32 v131, v8
	v_mov_b32_e32 v132, v8
	v_mov_b32_e32 v133, v8
	v_mov_b32_e32 v134, v8
	v_mov_b32_e32 v135, v8
	s_cmp_lt_u32 s3, 4
	s_cbranch_scc0 .Lgsp_8
	s_setprio 1

;     __device__ __forceinline__ bool next(int i, pg8::Unit& u) const { if (c < 128 || i >= 2) return false; const int idx = (c - 128) * 2 + i; u.pm = idx >> 2; u.pn = idx & 3; return true; }
; template <class Epi, class Sched, bool ALIGN_EPI = false, bool SP2 = false, bool F16 = false>
; __device__ __forceinline__ void gemm_phase(PG8_LAS unsigned char* lds, const Gemm g, const Sched& S, const Epi& E, const int wid_in) {
;     ...
;         const bool has_next = S.next(ui + 1, nxt);
;         const char* nA = has_next ? (const char*)g.A + (size_t)nxt.pm * tstep : cA; const char* nB = has_next ? (const char*)g.Bt + (size_t)nxt.pn * tstep : cB;
;         for (int t = 0; t < nt; t += 2) {
.LBB0_1275:
	s_mov_b64 s[34:35], 0
	s_cmp_lt_u32 s3, 4
	s_cbranch_scc0 .Lgsp_9
	s_setprio 1

;     __device__ __forceinline__ bool next(int i, pg8::Unit& u) const { if (c < 128 || i >= 2) return false; const int idx = (c - 128) * 2 + i; u.pm = idx >> 2; u.pn = idx & 3; return true; }
; template <class Epi, class Sched, bool ALIGN_EPI = false, bool SP2 = false, bool F16 = false>
; __device__ __forceinline__ void gemm_phase(PG8_LAS unsigned char* lds, const Gemm g, const Sched& S, const Epi& E, const int wid_in) {
;     ...
;         const bool has_next = S.next(ui + 1, nxt);
;         const char* nA = has_next ? (const char*)g.A + (size_t)nxt.pm * tstep : cA; const char* nB = has_next ? (const char*)g.Bt + (size_t)nxt.pn * tstep : cB;
;     ...
; #pragma unroll
;         for (int a = 0; a < 2; ++a)
; #pragma unroll
;             for (int b = 0; b < 2; ++b)
; #pragma unroll
;                 for (int m = 0; m < 4; ++m)
; #pragma unroll
;                     for (int n = 0; n < 2; ++n) acc[a][b][m][n] = (f32x4){0.f, 0.f, 0.f, 0.f};
;         cur = nxt; cA = nA; cB = nB; ++ui;
.LBB0_1372:
	s_add_u32 s43, s44, 0x100
	v_mov_b32_e32 v0, 0
	s_addc_u32 s61, s45, 0
	s_mov_b32 s62, -2
	v_mov_b32_e32 v1, v0
	v_mov_b32_e32 v2, v0
	v_mov_b32_e32 v3, v0
	v_mov_b32_e32 v4, v0
	v_mov_b32_e32 v5, v0
	v_mov_b32_e32 v6, v0
	v_mov_b32_e32 v7, v0
	v_mov_b32_e32 v16, v0
	v_mov_b32_e32 v17, v0
	v_mov_b32_e32 v18, v0
	v_mov_b32_e32 v19, v0
	v_mov_b32_e32 v20, v0
	v_mov_b32_e32 v21, v0
	v_mov_b32_e32 v22, v0
	v_mov_b32_e32 v23, v0
	v_mov_b32_e32 v32, v0
	v_mov_b32_e32 v33, v0
	v_mov_b32_e32 v34, v0
	v_mov_b32_e32 v35, v0
	v_mov_b32_e32 v36, v0
	v_mov_b32_e32 v37, v0
	v_mov_b32_e32 v38, v0
	v_mov_b32_e32 v39, v0
	v_mov_b32_e32 v48, v0
	v_mov_b32_e32 v49, v0
	v_mov_b32_e32 v50, v0
	v_mov_b32_e32 v51, v0
	v_mov_b32_e32 v52, v0
	v_mov_b32_e32 v53, v0
	v_mov_b32_e32 v54, v0
	v_mov_b32_e32 v55, v0
	v_mov_b32_e32 v8, v0
	v_mov_b32_e32 v9, v0
	v_mov_b32_e32 v10, v0
	v_mov_b32_e32 v11, v0
	v_mov_b32_e32 v12, v0
	v_mov_b32_e32 v13, v0
	v_mov_b32_e32 v14, v0
	v_mov_b32_e32 v15, v0
	v_mov_b32_e32 v24, v0
	v_mov_b32_e32 v25, v0
	v_mov_b32_e32 v26, v0
	v_mov_b32_e32 v27, v0
	v_mov_b32_e32 v28, v0
	v_mov_b32_e32 v29, v0
	v_mov_b32_e32 v30, v0
	v_mov_b32_e32 v31, v0
	v_mov_b32_e32 v40, v0
	v_mov_b32_e32 v41, v0
	v_mov_b32_e32 v42, v0
	v_mov_b32_e32 v43, v0
	v_mov_b32_e32 v44, v0
	v_mov_b32_e32 v45, v0
	v_mov_b32_e32 v46, v0
	v_mov_b32_e32 v47, v0
	v_mov_b32_e32 v56, v0
	v_mov_b32_e32 v57, v0
	v_mov_b32_e32 v58, v0
	v_mov_b32_e32 v59, v0
	v_mov_b32_e32 v60, v0
	v_mov_b32_e32 v61, v0
	v_mov_b32_e32 v62, v0
	v_mov_b32_e32 v63, v0
	v_mov_b32_e32 v64, v0
	v_mov_b32_e32 v65, v0
	v_mov_b32_e32 v66, v0
	v_mov_b32_e32 v67, v0
	v_mov_b32_e32 v68, v0
	v_mov_b32_e32 v69, v0
	v_mov_b32_e32 v70, v0
	v_mov_b32_e32 v71, v0
	v_mov_b32_e32 v80, v0
	v_mov_b32_e32 v81, v0
	v_mov_b32_e32 v82, v0
	v_mov_b32_e32 v83, v0
	v_mov_b32_e32 v84, v0
	v_mov_b32_e32 v85, v0
	v_mov_b32_e32 v86, v0
	v_mov_b32_e32 v87, v0
	v_mov_b32_e32 v96, v0
	v_mov_b32_e32 v97, v0
	v_mov_b32_e32 v98, v0
	v_mov_b32_e32 v99, v0
	v_mov_b32_e32 v100, v0
	v_mov_b32_e32 v101, v0
	v_mov_b32_e32 v102, v0
	v_mov_b32_e32 v103, v0
	v_mov_b32_e32 v112, v0
	v_mov_b32_e32 v113, v0
	v_mov_b32_e32 v114, v0
	v_mov_b32_e32 v115, v0
	v_mov_b32_e32 v116, v0
	v_mov_b32_e32 v117, v0
	v_mov_b32_e32 v118, v0
	v_mov_b32_e32 v119, v0
	v_mov_b32_e32 v72, v0
	v_mov_b32_e32 v73, v0
	v_mov_b32_e32 v74, v0
	v_mov_b32_e32 v75, v0
	v_mov_b32_e32 v76, v0
	v_mov_b32_e32 v77, v0
	v_mov_b32_e32 v78, v0
	v_mov_b32_e32 v79, v0
	v_mov_b32_e32 v88, v0
	v_mov_b32_e32 v89, v0
	v_mov_b32_e32 v90, v0
	v_mov_b32_e32 v91, v0
	v_mov_b32_e32 v92, v0
	v_mov_b32_e32 v93, v0
	v_mov_b32_e32 v94, v0
	v_mov_b32_e32 v95, v0
	v_mov_b32_e32 v104, v0
	v_mov_b32_e32 v105, v0
	v_mov_b32_e32 v106, v0
	v_mov_b32_e32 v107, v0
	v_mov_b32_e32 v108, v0
	v_mov_b32_e32 v109, v0
	v_mov_b32_e32 v110, v0
	v_mov_b32_e32 v111, v0
	v_mov_b32_e32 v120, v0
	v_mov_b32_e32 v121, v0
	v_mov_b32_e32 v122, v0
	v_mov_b32_e32 v123, v0
	v_mov_b32_e32 v124, v0
	v_mov_b32_e32 v125, v0
	v_mov_b32_e32 v126, v0
	v_mov_b32_e32 v127, v0
	s_cmp_lt_u32 s3, 4
	s_cbranch_scc0 .Lgsp_10
	s_setprio 1

;     __device__ __forceinline__ bool next(int i, pg8::Unit& u) const { if (c < 128 || i >= 2) return false; const int idx = (c - 128) * 2 + i; u.pm = idx >> 2; u.pn = idx & 3; return true; }
; template <class Epi, class Sched, bool ALIGN_EPI = false, bool SP2 = false, bool F16 = false>
; __device__ __forceinline__ void gemm_phase(PG8_LAS unsigned char* lds, const Gemm g, const Sched& S, const Epi& E, const int wid_in) {
;     ...
;         const bool has_next = S.next(ui + 1, nxt);
;         const char* nA = has_next ? (const char*)g.A + (size_t)nxt.pm * tstep : cA; const char* nB = has_next ? (const char*)g.Bt + (size_t)nxt.pn * tstep : cB;
;     ...
; #pragma unroll
;         for (int a = 0; a < 2; ++a)
; #pragma unroll
;             for (int b = 0; b < 2; ++b)
; #pragma unroll
;                 for (int m = 0; m < 4; ++m)
; #pragma unroll
;                     for (int n = 0; n < 2; ++n) acc[a][b][m][n] = (f32x4){0.f, 0.f, 0.f, 0.f};
;         cur = nxt; cA = nA; cB = nB; ++ui;
.LBB0_1468:
	s_ashr_i32 s45, s44, 31
	s_lshl_b64 s[14:15], s[44:45], 19
	s_add_u32 s46, s12, s14
	s_addc_u32 s47, s13, s15
	s_and_b64 s[14:15], s[10:11], exec
	s_cselect_b32 s14, s47, s53
	s_cselect_b32 s15, s46, s52
	s_ashr_i32 s37, s36, 31
	s_lshl_b64 s[40:41], s[36:37], 19
	s_add_u32 s48, s21, s40
	s_addc_u32 s49, s58, s41
	s_and_b64 s[40:41], s[10:11], exec
	s_cselect_b32 s37, s49, s55
	s_cselect_b32 s40, s48, s54
	s_add_u32 s52, s52, 0x40080
	s_addc_u32 s53, s53, 0
	s_add_u32 s41, s54, 0x100
	v_mov_b32_e32 v0, 0
	s_addc_u32 s42, s55, 0
	s_mov_b32 s43, -2
	v_mov_b32_e32 v1, v0
	v_mov_b32_e32 v2, v0
	v_mov_b32_e32 v3, v0
	v_mov_b32_e32 v4, v0
	v_mov_b32_e32 v5, v0
	v_mov_b32_e32 v6, v0
	v_mov_b32_e32 v7, v0
	v_mov_b32_e32 v16, v0
	v_mov_b32_e32 v17, v0
	v_mov_b32_e32 v18, v0
	v_mov_b32_e32 v19, v0
	v_mov_b32_e32 v20, v0
	v_mov_b32_e32 v21, v0
	v_mov_b32_e32 v22, v0
	v_mov_b32_e32 v23, v0
	v_mov_b32_e32 v32, v0
	v_mov_b32_e32 v33, v0
	v_mov_b32_e32 v34, v0
	v_mov_b32_e32 v35, v0
	v_mov_b32_e32 v36, v0
	v_mov_b32_e32 v37, v0
	v_mov_b32_e32 v38, v0
	v_mov_b32_e32 v39, v0
	v_mov_b32_e32 v48, v0
	v_mov_b32_e32 v49, v0
	v_mov_b32_e32 v50, v0
	v_mov_b32_e32 v51, v0
	v_mov_b32_e32 v52, v0
	v_mov_b32_e32 v53, v0
	v_mov_b32_e32 v54, v0
	v_mov_b32_e32 v55, v0
	v_mov_b32_e32 v8, v0
	v_mov_b32_e32 v9, v0
	v_mov_b32_e32 v10, v0
	v_mov_b32_e32 v11, v0
	v_mov_b32_e32 v12, v0
	v_mov_b32_e32 v13, v0
	v_mov_b32_e32 v14, v0
	v_mov_b32_e32 v15, v0
	v_mov_b32_e32 v24, v0
	v_mov_b32_e32 v25, v0
	v_mov_b32_e32 v26, v0
	v_mov_b32_e32 v27, v0
	v_mov_b32_e32 v28, v0
	v_mov_b32_e32 v29, v0
	v_mov_b32_e32 v30, v0
	v_mov_b32_e32 v31, v0
	v_mov_b32_e32 v40, v0
	v_mov_b32_e32 v41, v0
	v_mov_b32_e32 v42, v0
	v_mov_b32_e32 v43, v0
	v_mov_b32_e32 v44, v0
	v_mov_b32_e32 v45, v0
	v_mov_b32_e32 v46, v0
	v_mov_b32_e32 v47, v0
	v_mov_b32_e32 v56, v0
	v_mov_b32_e32 v57, v0
	v_mov_b32_e32 v58, v0
	v_mov_b32_e32 v59, v0
	v_mov_b32_e32 v60, v0
	v_mov_b32_e32 v61, v0
	v_mov_b32_e32 v62, v0
	v_mov_b32_e32 v63, v0
	v_mov_b32_e32 v64, v0
	v_mov_b32_e32 v65, v0
	v_mov_b32_e32 v66, v0
	v_mov_b32_e32 v67, v0
	v_mov_b32_e32 v68, v0
	v_mov_b32_e32 v69, v0
	v_mov_b32_e32 v70, v0
	v_mov_b32_e32 v71, v0
	v_mov_b32_e32 v80, v0
	v_mov_b32_e32 v81, v0
	v_mov_b32_e32 v82, v0
	v_mov_b32_e32 v83, v0
	v_mov_b32_e32 v84, v0
	v_mov_b32_e32 v85, v0
	v_mov_b32_e32 v86, v0
	v_mov_b32_e32 v87, v0
	v_mov_b32_e32 v96, v0
	v_mov_b32_e32 v97, v0
	v_mov_b32_e32 v98, v0
	v_mov_b32_e32 v99, v0
	v_mov_b32_e32 v100, v0
	v_mov_b32_e32 v101, v0
	v_mov_b32_e32 v102, v0
	v_mov_b32_e32 v103, v0
	v_mov_b32_e32 v120, v0
	v_mov_b32_e32 v121, v0
	v_mov_b32_e32 v122, v0
	v_mov_b32_e32 v123, v0
	v_mov_b32_e32 v124, v0
	v_mov_b32_e32 v125, v0
	v_mov_b32_e32 v126, v0
	v_mov_b32_e32 v127, v0
	v_mov_b32_e32 v72, v0
	v_mov_b32_e32 v73, v0
	v_mov_b32_e32 v74, v0
	v_mov_b32_e32 v75, v0
	v_mov_b32_e32 v76, v0
	v_mov_b32_e32 v77, v0
	v_mov_b32_e32 v78, v0
	v_mov_b32_e32 v79, v0
	v_mov_b32_e32 v88, v0
	v_mov_b32_e32 v89, v0
	v_mov_b32_e32 v90, v0
	v_mov_b32_e32 v91, v0
	v_mov_b32_e32 v92, v0
	v_mov_b32_e32 v93, v0
	v_mov_b32_e32 v94, v0
	v_mov_b32_e32 v95, v0
	v_mov_b32_e32 v104, v0
	v_mov_b32_e32 v105, v0
	v_mov_b32_e32 v106, v0
	v_mov_b32_e32 v107, v0
	v_mov_b32_e32 v108, v0
	v_mov_b32_e32 v109, v0
	v_mov_b32_e32 v110, v0
	v_mov_b32_e32 v111, v0
	v_mov_b32_e32 v136, v0
	v_mov_b32_e32 v137, v0
	v_mov_b32_e32 v138, v0
	v_mov_b32_e32 v139, v0
	v_mov_b32_e32 v140, v0
	v_mov_b32_e32 v141, v0
	v_mov_b32_e32 v142, v0
	v_mov_b32_e32 v143, v0
	s_cmp_lt_u32 s3, 4
	s_cbranch_scc0 .Lgsp_11
	s_setprio 1

;     __device__ __forceinline__ bool next(int i, pg8::Unit& u) const { if (c < 128 || i >= 2) return false; const int idx = (c - 128) * 2 + i; u.pm = idx >> 2; u.pn = idx & 3; return true; }
; template <class Epi, class Sched, bool ALIGN_EPI = false, bool SP2 = false, bool F16 = false>
; __device__ __forceinline__ void gemm_phase(PG8_LAS unsigned char* lds, const Gemm g, const Sched& S, const Epi& E, const int wid_in) {
;     ...
;         const bool has_next = S.next(ui + 1, nxt);
;         const char* nA = has_next ? (const char*)g.A + (size_t)nxt.pm * tstep : cA; const char* nB = has_next ? (const char*)g.Bt + (size_t)nxt.pn * tstep : cB;
;     ...
; #pragma unroll
;         for (int a = 0; a < 2; ++a)
; #pragma unroll
;             for (int b = 0; b < 2; ++b)
; #pragma unroll
;                 for (int m = 0; m < 4; ++m)
; #pragma unroll
;                     for (int n = 0; n < 2; ++n) acc[a][b][m][n] = (f32x4){0.f, 0.f, 0.f, 0.f};
;         cur = nxt; cA = nA; cB = nB; ++ui;
.LBB0_1547:
	s_ashr_i32 s45, s44, 31
	s_lshl_b64 s[40:41], s[44:45], 19
	s_add_u32 s46, s62, s40
	s_addc_u32 s47, s63, s41
	s_and_b64 s[40:41], s[10:11], exec
	s_cselect_b32 s13, s47, s51
	s_cselect_b32 s31, s46, s50
	s_ashr_i32 s37, s36, 31
	s_lshl_b64 s[40:41], s[36:37], 19
	s_add_u32 s48, s64, s40
	s_addc_u32 s49, s65, s41
	s_and_b64 s[40:41], s[10:11], exec
	s_cselect_b32 s37, s49, s53
	s_cselect_b32 s40, s48, s52
	s_add_u32 s50, s50, 0x40080
	s_addc_u32 s51, s51, 0
	s_add_u32 s41, s52, 0x100
	v_mov_b32_e32 v0, 0
	s_addc_u32 s42, s53, 0
	s_mov_b32 s43, -2
	s_waitcnt lgkmcnt(0)
	v_mov_b32_e32 v1, v0
	v_mov_b32_e32 v2, v0
	v_mov_b32_e32 v3, v0
	v_mov_b32_e32 v4, v0
	v_mov_b32_e32 v5, v0
	v_mov_b32_e32 v6, v0
	v_mov_b32_e32 v7, v0
	v_mov_b32_e32 v16, v0
	v_mov_b32_e32 v17, v0
	v_mov_b32_e32 v18, v0
	v_mov_b32_e32 v19, v0
	v_mov_b32_e32 v20, v0
	v_mov_b32_e32 v21, v0
	v_mov_b32_e32 v22, v0
	v_mov_b32_e32 v23, v0
	v_mov_b32_e32 v32, v0
	v_mov_b32_e32 v33, v0
	v_mov_b32_e32 v34, v0
	v_mov_b32_e32 v35, v0
	v_mov_b32_e32 v36, v0
	v_mov_b32_e32 v37, v0
	v_mov_b32_e32 v38, v0
	v_mov_b32_e32 v39, v0
	v_mov_b32_e32 v48, v0
	v_mov_b32_e32 v49, v0
	v_mov_b32_e32 v50, v0
	v_mov_b32_e32 v51, v0
	v_mov_b32_e32 v52, v0
	v_mov_b32_e32 v53, v0
	v_mov_b32_e32 v54, v0
	v_mov_b32_e32 v55, v0
	v_mov_b32_e32 v8, v0
	v_mov_b32_e32 v9, v0
	v_mov_b32_e32 v10, v0
	v_mov_b32_e32 v11, v0
	v_mov_b32_e32 v12, v0
	v_mov_b32_e32 v13, v0
	v_mov_b32_e32 v14, v0
	v_mov_b32_e32 v15, v0
	v_mov_b32_e32 v24, v0
	v_mov_b32_e32 v25, v0
	v_mov_b32_e32 v26, v0
	v_mov_b32_e32 v27, v0
	v_mov_b32_e32 v28, v0
	v_mov_b32_e32 v29, v0
	v_mov_b32_e32 v30, v0
	v_mov_b32_e32 v31, v0
	v_mov_b32_e32 v40, v0
	v_mov_b32_e32 v41, v0
	v_mov_b32_e32 v42, v0
	v_mov_b32_e32 v43, v0
	v_mov_b32_e32 v44, v0
	v_mov_b32_e32 v45, v0
	v_mov_b32_e32 v46, v0
	v_mov_b32_e32 v47, v0
	v_mov_b32_e32 v56, v0
	v_mov_b32_e32 v57, v0
	v_mov_b32_e32 v58, v0
	v_mov_b32_e32 v59, v0
	v_mov_b32_e32 v60, v0
	v_mov_b32_e32 v61, v0
	v_mov_b32_e32 v62, v0
	v_mov_b32_e32 v63, v0
	v_mov_b32_e32 v64, v0
	v_mov_b32_e32 v65, v0
	v_mov_b32_e32 v66, v0
	v_mov_b32_e32 v67, v0
	v_mov_b32_e32 v68, v0
	v_mov_b32_e32 v69, v0
	v_mov_b32_e32 v70, v0
	v_mov_b32_e32 v71, v0
	v_mov_b32_e32 v80, v0
	v_mov_b32_e32 v81, v0
	v_mov_b32_e32 v82, v0
	v_mov_b32_e32 v83, v0
	v_mov_b32_e32 v84, v0
	v_mov_b32_e32 v85, v0
	v_mov_b32_e32 v86, v0
	v_mov_b32_e32 v87, v0
	v_mov_b32_e32 v96, v0
	v_mov_b32_e32 v97, v0
	v_mov_b32_e32 v98, v0
	v_mov_b32_e32 v99, v0
	v_mov_b32_e32 v100, v0
	v_mov_b32_e32 v101, v0
	v_mov_b32_e32 v102, v0
	v_mov_b32_e32 v103, v0
	v_mov_b32_e32 v112, v0
	v_mov_b32_e32 v113, v0
	v_mov_b32_e32 v114, v0
	v_mov_b32_e32 v115, v0
	v_mov_b32_e32 v116, v0
	v_mov_b32_e32 v117, v0
	v_mov_b32_e32 v118, v0
	v_mov_b32_e32 v119, v0
	v_mov_b32_e32 v72, v0
	v_mov_b32_e32 v73, v0
	v_mov_b32_e32 v74, v0
	v_mov_b32_e32 v75, v0
	v_mov_b32_e32 v76, v0
	v_mov_b32_e32 v77, v0
	v_mov_b32_e32 v78, v0
	v_mov_b32_e32 v79, v0
	v_mov_b32_e32 v88, v0
	v_mov_b32_e32 v89, v0
	v_mov_b32_e32 v90, v0
	v_mov_b32_e32 v91, v0
	v_mov_b32_e32 v92, v0
	v_mov_b32_e32 v93, v0
	v_mov_b32_e32 v94, v0
	v_mov_b32_e32 v95, v0
	v_mov_b32_e32 v104, v0
	v_mov_b32_e32 v105, v0
	v_mov_b32_e32 v106, v0
	v_mov_b32_e32 v107, v0
	v_mov_b32_e32 v108, v0
	v_mov_b32_e32 v109, v0
	v_mov_b32_e32 v110, v0
	v_mov_b32_e32 v111, v0
	v_mov_b32_e32 v120, v0
	v_mov_b32_e32 v121, v0
	v_mov_b32_e32 v122, v0
	v_mov_b32_e32 v123, v0
	v_mov_b32_e32 v124, v0
	v_mov_b32_e32 v125, v0
	v_mov_b32_e32 v126, v0
	v_mov_b32_e32 v127, v0
	s_cmp_lt_u32 s3, 4
	s_cbranch_scc0 .Lgsp_12
	s_setprio 1

;     __device__ __forceinline__ bool next(int i, pg8::Unit& u) const { if (c < 128 || i >= 2) return false; const int idx = (c - 128) * 2 + i; u.pm = idx >> 2; u.pn = idx & 3; return true; }
; template <class Epi, class Sched, bool ALIGN_EPI = false, bool SP2 = false, bool F16 = false>
; __device__ __forceinline__ void gemm_phase(PG8_LAS unsigned char* lds, const Gemm g, const Sched& S, const Epi& E, const int wid_in) {
;     ...
;         const bool has_next = S.next(ui + 1, nxt);
;         const char* nA = has_next ? (const char*)g.A + (size_t)nxt.pm * tstep : cA; const char* nB = has_next ? (const char*)g.Bt + (size_t)nxt.pn * tstep : cB;
;     ...
; #pragma unroll
;         for (int a = 0; a < 2; ++a)
; #pragma unroll
;             for (int b = 0; b < 2; ++b)
; #pragma unroll
;                 for (int m = 0; m < 4; ++m)
; #pragma unroll
;                     for (int n = 0; n < 2; ++n) acc[a][b][m][n] = (f32x4){0.f, 0.f, 0.f, 0.f};
;         cur = nxt; cA = nA; cB = nB; ++ui;
.LBB0_1831:
	s_ashr_i32 s35, s34, 31
	s_lshl_b64 s[36:37], s[34:35], 19
	s_add_u32 s36, s15, s36
	s_addc_u32 s37, s19, s37
	s_and_b64 s[42:43], s[10:11], exec
	s_cselect_b32 s35, s37, s49
	s_cselect_b32 s42, s36, s48
	s_ashr_i32 s31, s30, 31
	s_lshl_b64 s[44:45], s[30:31], 19
	s_add_u32 s44, s21, s44
	s_addc_u32 s45, s40, s45
	s_and_b64 s[52:53], s[10:11], exec
	s_cselect_b32 s31, s45, s51
	s_cselect_b32 s43, s44, s50
	s_add_u32 s48, s48, 0x40080
	s_addc_u32 s49, s49, 0
	s_add_u32 s47, s50, 0x100
	v_mov_b32_e32 v0, 0
	s_addc_u32 s60, s51, 0
	s_mov_b32 s61, -2
	v_mov_b32_e32 v1, v0
	v_mov_b32_e32 v2, v0
	v_mov_b32_e32 v3, v0
	v_mov_b32_e32 v4, v0
	v_mov_b32_e32 v5, v0
	v_mov_b32_e32 v6, v0
	v_mov_b32_e32 v7, v0
	v_mov_b32_e32 v16, v0
	v_mov_b32_e32 v17, v0
	v_mov_b32_e32 v18, v0
	v_mov_b32_e32 v19, v0
	v_mov_b32_e32 v20, v0
	v_mov_b32_e32 v21, v0
	v_mov_b32_e32 v22, v0
	v_mov_b32_e32 v23, v0
	v_mov_b32_e32 v32, v0
	v_mov_b32_e32 v33, v0
	v_mov_b32_e32 v34, v0
	v_mov_b32_e32 v35, v0
	v_mov_b32_e32 v36, v0
	v_mov_b32_e32 v37, v0
	v_mov_b32_e32 v38, v0
	v_mov_b32_e32 v39, v0
	v_mov_b32_e32 v48, v0
	v_mov_b32_e32 v49, v0
	v_mov_b32_e32 v50, v0
	v_mov_b32_e32 v51, v0
	v_mov_b32_e32 v52, v0
	v_mov_b32_e32 v53, v0
	v_mov_b32_e32 v54, v0
	v_mov_b32_e32 v55, v0
	v_mov_b32_e32 v8, v0
	v_mov_b32_e32 v9, v0
	v_mov_b32_e32 v10, v0
	v_mov_b32_e32 v11, v0
	v_mov_b32_e32 v12, v0
	v_mov_b32_e32 v13, v0
	v_mov_b32_e32 v14, v0
	v_mov_b32_e32 v15, v0
	v_mov_b32_e32 v24, v0
	v_mov_b32_e32 v25, v0
	v_mov_b32_e32 v26, v0
	v_mov_b32_e32 v27, v0
	v_mov_b32_e32 v28, v0
	v_mov_b32_e32 v29, v0
	v_mov_b32_e32 v30, v0
	v_mov_b32_e32 v31, v0
	v_mov_b32_e32 v40, v0
	v_mov_b32_e32 v41, v0
	v_mov_b32_e32 v42, v0
	v_mov_b32_e32 v43, v0
	v_mov_b32_e32 v44, v0
	v_mov_b32_e32 v45, v0
	v_mov_b32_e32 v46, v0
	v_mov_b32_e32 v47, v0
	v_mov_b32_e32 v56, v0
	v_mov_b32_e32 v57, v0
	v_mov_b32_e32 v58, v0
	v_mov_b32_e32 v59, v0
	v_mov_b32_e32 v60, v0
	v_mov_b32_e32 v61, v0
	v_mov_b32_e32 v62, v0
	v_mov_b32_e32 v63, v0
	v_mov_b32_e32 v64, v0
	v_mov_b32_e32 v65, v0
	v_mov_b32_e32 v66, v0
	v_mov_b32_e32 v67, v0
	v_mov_b32_e32 v68, v0
	v_mov_b32_e32 v69, v0
	v_mov_b32_e32 v70, v0
	v_mov_b32_e32 v71, v0
	v_mov_b32_e32 v80, v0
	v_mov_b32_e32 v81, v0
	v_mov_b32_e32 v82, v0
	v_mov_b32_e32 v83, v0
	v_mov_b32_e32 v84, v0
	v_mov_b32_e32 v85, v0
	v_mov_b32_e32 v86, v0
	v_mov_b32_e32 v87, v0
	v_mov_b32_e32 v96, v0
	v_mov_b32_e32 v97, v0
	v_mov_b32_e32 v98, v0
	v_mov_b32_e32 v99, v0
	v_mov_b32_e32 v100, v0
	v_mov_b32_e32 v101, v0
	v_mov_b32_e32 v102, v0
	v_mov_b32_e32 v103, v0
	v_mov_b32_e32 v112, v0
	v_mov_b32_e32 v113, v0
	v_mov_b32_e32 v114, v0
	v_mov_b32_e32 v115, v0
	v_mov_b32_e32 v116, v0
	v_mov_b32_e32 v117, v0
	v_mov_b32_e32 v118, v0
	v_mov_b32_e32 v119, v0
	v_mov_b32_e32 v72, v0
	v_mov_b32_e32 v73, v0
	v_mov_b32_e32 v74, v0
	v_mov_b32_e32 v75, v0
	v_mov_b32_e32 v76, v0
	v_mov_b32_e32 v77, v0
	v_mov_b32_e32 v78, v0
	v_mov_b32_e32 v79, v0
	v_mov_b32_e32 v88, v0
	v_mov_b32_e32 v89, v0
	v_mov_b32_e32 v90, v0
	v_mov_b32_e32 v91, v0
	v_mov_b32_e32 v92, v0
	v_mov_b32_e32 v93, v0
	v_mov_b32_e32 v94, v0
	v_mov_b32_e32 v95, v0
	v_mov_b32_e32 v104, v0
	v_mov_b32_e32 v105, v0
	v_mov_b32_e32 v106, v0
	v_mov_b32_e32 v107, v0
	v_mov_b32_e32 v108, v0
	v_mov_b32_e32 v109, v0
	v_mov_b32_e32 v110, v0
	v_mov_b32_e32 v111, v0
	v_mov_b32_e32 v120, v0
	v_mov_b32_e32 v121, v0
	v_mov_b32_e32 v122, v0
	v_mov_b32_e32 v123, v0
	v_mov_b32_e32 v124, v0
	v_mov_b32_e32 v125, v0
	v_mov_b32_e32 v126, v0
	v_mov_b32_e32 v127, v0
	s_cmp_lt_u32 s3, 4
	s_cbranch_scc0 .Lgsp_13
	s_setprio 1

;     __device__ __forceinline__ bool next(int i, pg8::Unit& u) const { if (c < 128 || i >= 2) return false; const int idx = (c - 128) * 2 + i; u.pm = idx >> 2; u.pn = idx & 3; return true; }
; template <class Epi, class Sched, bool ALIGN_EPI = false, bool SP2 = false, bool F16 = false>
; __device__ __forceinline__ void gemm_phase(PG8_LAS unsigned char* lds, const Gemm g, const Sched& S, const Epi& E, const int wid_in) {
;     ...
;         const bool has_next = S.next(ui + 1, nxt);
;         const char* nA = has_next ? (const char*)g.A + (size_t)nxt.pm * tstep : cA; const char* nB = has_next ? (const char*)g.Bt + (size_t)nxt.pn * tstep : cB;
;     ...
; #pragma unroll
;         for (int a = 0; a < 2; ++a)
; #pragma unroll
;             for (int b = 0; b < 2; ++b)
; #pragma unroll
;                 for (int m = 0; m < 4; ++m)
; #pragma unroll
;                     for (int n = 0; n < 2; ++n) acc[a][b][m][n] = (f32x4){0.f, 0.f, 0.f, 0.f};
;         cur = nxt; cA = nA; cB = nB; ++ui;
.LBB0_1908:
	s_ashr_i32 s29, s28, 31
	s_lshl_b64 s[30:31], s[28:29], 19
	s_add_u32 s30, s21, s30
	s_addc_u32 s31, s40, s31
	s_and_b64 s[34:35], s[10:11], exec
	s_cselect_b32 s29, s31, s47
	s_cselect_b32 s42, s30, s46
	s_ashr_i32 s27, s26, 31
	s_lshl_b64 s[34:35], s[26:27], 19
	s_add_u32 s34, s41, s34
	s_addc_u32 s35, s52, s35
	s_and_b64 s[50:51], s[10:11], exec
	s_cselect_b32 s27, s35, s49
	s_cselect_b32 s43, s34, s48
	s_add_u32 s46, s46, 0x40080
	s_addc_u32 s47, s47, 0
	s_add_u32 s45, s48, 0x100
	v_mov_b32_e32 v8, 0
	s_addc_u32 s63, s49, 0
	s_mov_b32 s64, -2
	v_mov_b32_e32 v9, v8
	v_mov_b32_e32 v10, v8
	v_mov_b32_e32 v11, v8
	v_mov_b32_e32 v12, v8
	v_mov_b32_e32 v13, v8
	v_mov_b32_e32 v14, v8
	v_mov_b32_e32 v15, v8
	v_mov_b32_e32 v24, v8
	v_mov_b32_e32 v25, v8
	v_mov_b32_e32 v26, v8
	v_mov_b32_e32 v27, v8
	v_mov_b32_e32 v28, v8
	v_mov_b32_e32 v29, v8
	v_mov_b32_e32 v30, v8
	v_mov_b32_e32 v31, v8
	v_mov_b32_e32 v40, v8
	v_mov_b32_e32 v41, v8
	v_mov_b32_e32 v42, v8
	v_mov_b32_e32 v43, v8
	v_mov_b32_e32 v44, v8
	v_mov_b32_e32 v45, v8
	v_mov_b32_e32 v46, v8
	v_mov_b32_e32 v47, v8
	v_mov_b32_e32 v56, v8
	v_mov_b32_e32 v57, v8
	v_mov_b32_e32 v58, v8
	v_mov_b32_e32 v59, v8
	v_mov_b32_e32 v60, v8
	v_mov_b32_e32 v61, v8
	v_mov_b32_e32 v62, v8
	v_mov_b32_e32 v63, v8
	v_mov_b32_e32 v16, v8
	v_mov_b32_e32 v17, v8
	v_mov_b32_e32 v18, v8
	v_mov_b32_e32 v19, v8
	v_mov_b32_e32 v20, v8
	v_mov_b32_e32 v21, v8
	v_mov_b32_e32 v22, v8
	v_mov_b32_e32 v23, v8
	v_mov_b32_e32 v32, v8
	v_mov_b32_e32 v33, v8
	v_mov_b32_e32 v34, v8
	v_mov_b32_e32 v35, v8
	v_mov_b32_e32 v36, v8
	v_mov_b32_e32 v37, v8
	v_mov_b32_e32 v38, v8
	v_mov_b32_e32 v39, v8
	v_mov_b32_e32 v48, v8
	v_mov_b32_e32 v49, v8
	v_mov_b32_e32 v50, v8
	v_mov_b32_e32 v51, v8
	v_mov_b32_e32 v52, v8
	v_mov_b32_e32 v53, v8
	v_mov_b32_e32 v54, v8
	v_mov_b32_e32 v55, v8
	v_mov_b32_e32 v64, v8
	v_mov_b32_e32 v65, v8
	v_mov_b32_e32 v66, v8
	v_mov_b32_e32 v67, v8
	v_mov_b32_e32 v68, v8
	v_mov_b32_e32 v69, v8
	v_mov_b32_e32 v70, v8
	v_mov_b32_e32 v71, v8
	v_mov_b32_e32 v72, v8
	v_mov_b32_e32 v73, v8
	v_mov_b32_e32 v74, v8
	v_mov_b32_e32 v75, v8
	v_mov_b32_e32 v76, v8
	v_mov_b32_e32 v77, v8
	v_mov_b32_e32 v78, v8
	v_mov_b32_e32 v79, v8
	v_mov_b32_e32 v88, v8
	v_mov_b32_e32 v89, v8
	v_mov_b32_e32 v90, v8
	v_mov_b32_e32 v91, v8
	v_mov_b32_e32 v92, v8
	v_mov_b32_e32 v93, v8
	v_mov_b32_e32 v94, v8
	v_mov_b32_e32 v95, v8
	v_mov_b32_e32 v104, v8
	v_mov_b32_e32 v105, v8
	v_mov_b32_e32 v106, v8
	v_mov_b32_e32 v107, v8
	v_mov_b32_e32 v108, v8
	v_mov_b32_e32 v109, v8
	v_mov_b32_e32 v110, v8
	v_mov_b32_e32 v111, v8
	v_mov_b32_e32 v120, v8
	v_mov_b32_e32 v121, v8
	v_mov_b32_e32 v122, v8
	v_mov_b32_e32 v123, v8
	v_mov_b32_e32 v124, v8
	v_mov_b32_e32 v125, v8
	v_mov_b32_e32 v126, v8
	v_mov_b32_e32 v127, v8
	v_mov_b32_e32 v80, v8
	v_mov_b32_e32 v81, v8
	v_mov_b32_e32 v82, v8
	v_mov_b32_e32 v83, v8
	v_mov_b32_e32 v84, v8
	v_mov_b32_e32 v85, v8
	v_mov_b32_e32 v86, v8
	v_mov_b32_e32 v87, v8
	v_mov_b32_e32 v96, v8
	v_mov_b32_e32 v97, v8
	v_mov_b32_e32 v98, v8
	v_mov_b32_e32 v99, v8
	v_mov_b32_e32 v100, v8
	v_mov_b32_e32 v101, v8
	v_mov_b32_e32 v102, v8
	v_mov_b32_e32 v103, v8
	v_mov_b32_e32 v112, v8
	v_mov_b32_e32 v113, v8
	v_mov_b32_e32 v114, v8
	v_mov_b32_e32 v115, v8
	v_mov_b32_e32 v116, v8
	v_mov_b32_e32 v117, v8
	v_mov_b32_e32 v118, v8
	v_mov_b32_e32 v119, v8
	v_mov_b32_e32 v128, v8
	v_mov_b32_e32 v129, v8
	v_mov_b32_e32 v130, v8
	v_mov_b32_e32 v131, v8
	v_mov_b32_e32 v132, v8
	v_mov_b32_e32 v133, v8
	v_mov_b32_e32 v134, v8
	v_mov_b32_e32 v135, v8
	s_cmp_lt_u32 s3, 4
	s_cbranch_scc0 .Lgsp_14
	s_setprio 1

;     __device__ __forceinline__ bool next(int i, pg8::Unit& u) const { if (c < 128 || i >= 2) return false; const int idx = (c - 128) * 2 + i; u.pm = idx >> 2; u.pn = idx & 3; return true; }
; template <class Epi, class Sched, bool ALIGN_EPI = false, bool SP2 = false, bool F16 = false>
; __device__ __forceinline__ void gemm_phase(PG8_LAS unsigned char* lds, const Gemm g, const Sched& S, const Epi& E, const int wid_in) {
;     ...
;         const bool has_next = S.next(ui + 1, nxt);
;         const char* nA = has_next ? (const char*)g.A + (size_t)nxt.pm * tstep : cA; const char* nB = has_next ? (const char*)g.Bt + (size_t)nxt.pn * tstep : cB;
;     ...
; #pragma unroll
;         for (int a = 0; a < 2; ++a)
; #pragma unroll
;             for (int b = 0; b < 2; ++b)
; #pragma unroll
;                 for (int m = 0; m < 4; ++m)
; #pragma unroll
;                     for (int n = 0; n < 2; ++n) acc[a][b][m][n] = (f32x4){0.f, 0.f, 0.f, 0.f};
;         cur = nxt; cA = nA; cB = nB; ++ui;
.LBB0_2039:
	s_add_u32 s43, s44, 0x100
	v_mov_b32_e32 v0, 0
	s_addc_u32 s58, s45, 0
	s_mov_b32 s59, -2
	v_mov_b32_e32 v1, v0
	v_mov_b32_e32 v2, v0
	v_mov_b32_e32 v3, v0
	v_mov_b32_e32 v4, v0
	v_mov_b32_e32 v5, v0
	v_mov_b32_e32 v6, v0
	v_mov_b32_e32 v7, v0
	v_mov_b32_e32 v16, v0
	v_mov_b32_e32 v17, v0
	v_mov_b32_e32 v18, v0
	v_mov_b32_e32 v19, v0
	v_mov_b32_e32 v20, v0
	v_mov_b32_e32 v21, v0
	v_mov_b32_e32 v22, v0
	v_mov_b32_e32 v23, v0
	v_mov_b32_e32 v32, v0
	v_mov_b32_e32 v33, v0
	v_mov_b32_e32 v34, v0
	v_mov_b32_e32 v35, v0
	v_mov_b32_e32 v36, v0
	v_mov_b32_e32 v37, v0
	v_mov_b32_e32 v38, v0
	v_mov_b32_e32 v39, v0
	v_mov_b32_e32 v48, v0
	v_mov_b32_e32 v49, v0
	v_mov_b32_e32 v50, v0
	v_mov_b32_e32 v51, v0
	v_mov_b32_e32 v52, v0
	v_mov_b32_e32 v53, v0
	v_mov_b32_e32 v54, v0
	v_mov_b32_e32 v55, v0
	v_mov_b32_e32 v8, v0
	v_mov_b32_e32 v9, v0
	v_mov_b32_e32 v10, v0
	v_mov_b32_e32 v11, v0
	v_mov_b32_e32 v12, v0
	v_mov_b32_e32 v13, v0
	v_mov_b32_e32 v14, v0
	v_mov_b32_e32 v15, v0
	v_mov_b32_e32 v24, v0
	v_mov_b32_e32 v25, v0
	v_mov_b32_e32 v26, v0
	v_mov_b32_e32 v27, v0
	v_mov_b32_e32 v28, v0
	v_mov_b32_e32 v29, v0
	v_mov_b32_e32 v30, v0
	v_mov_b32_e32 v31, v0
	v_mov_b32_e32 v40, v0
	v_mov_b32_e32 v41, v0
	v_mov_b32_e32 v42, v0
	v_mov_b32_e32 v43, v0
	v_mov_b32_e32 v44, v0
	v_mov_b32_e32 v45, v0
	v_mov_b32_e32 v46, v0
	v_mov_b32_e32 v47, v0
	v_mov_b32_e32 v56, v0
	v_mov_b32_e32 v57, v0
	v_mov_b32_e32 v58, v0
	v_mov_b32_e32 v59, v0
	v_mov_b32_e32 v60, v0
	v_mov_b32_e32 v61, v0
	v_mov_b32_e32 v62, v0
	v_mov_b32_e32 v63, v0
	v_mov_b32_e32 v64, v0
	v_mov_b32_e32 v65, v0
	v_mov_b32_e32 v66, v0
	v_mov_b32_e32 v67, v0
	v_mov_b32_e32 v68, v0
	v_mov_b32_e32 v69, v0
	v_mov_b32_e32 v70, v0
	v_mov_b32_e32 v71, v0
	v_mov_b32_e32 v80, v0
	v_mov_b32_e32 v81, v0
	v_mov_b32_e32 v82, v0
	v_mov_b32_e32 v83, v0
	v_mov_b32_e32 v84, v0
	v_mov_b32_e32 v85, v0
	v_mov_b32_e32 v86, v0
	v_mov_b32_e32 v87, v0
	v_mov_b32_e32 v96, v0
	v_mov_b32_e32 v97, v0
	v_mov_b32_e32 v98, v0
	v_mov_b32_e32 v99, v0
	v_mov_b32_e32 v100, v0
	v_mov_b32_e32 v101, v0
	v_mov_b32_e32 v102, v0
	v_mov_b32_e32 v103, v0
	v_mov_b32_e32 v112, v0
	v_mov_b32_e32 v113, v0
	v_mov_b32_e32 v114, v0
	v_mov_b32_e32 v115, v0
	v_mov_b32_e32 v116, v0
	v_mov_b32_e32 v117, v0
	v_mov_b32_e32 v118, v0
	v_mov_b32_e32 v119, v0
	v_mov_b32_e32 v72, v0
	v_mov_b32_e32 v73, v0
	v_mov_b32_e32 v74, v0
	v_mov_b32_e32 v75, v0
	v_mov_b32_e32 v76, v0
	v_mov_b32_e32 v77, v0
	v_mov_b32_e32 v78, v0
	v_mov_b32_e32 v79, v0
	v_mov_b32_e32 v88, v0
	v_mov_b32_e32 v89, v0
	v_mov_b32_e32 v90, v0
	v_mov_b32_e32 v91, v0
	v_mov_b32_e32 v92, v0
	v_mov_b32_e32 v93, v0
	v_mov_b32_e32 v94, v0
	v_mov_b32_e32 v95, v0
	v_mov_b32_e32 v104, v0
	v_mov_b32_e32 v105, v0
	v_mov_b32_e32 v106, v0
	v_mov_b32_e32 v107, v0
	v_mov_b32_e32 v108, v0
	v_mov_b32_e32 v109, v0
	v_mov_b32_e32 v110, v0
	v_mov_b32_e32 v111, v0
	v_mov_b32_e32 v120, v0
	v_mov_b32_e32 v121, v0
	v_mov_b32_e32 v122, v0
	v_mov_b32_e32 v123, v0
	v_mov_b32_e32 v124, v0
	v_mov_b32_e32 v125, v0
	v_mov_b32_e32 v126, v0
	v_mov_b32_e32 v127, v0
	s_cmp_lt_u32 s3, 4
	s_cbranch_scc0 .Lgsp_16
	s_setprio 1

;     __device__ __forceinline__ bool next(int i, pg8::Unit& u) const { if (c < 128 || i >= 2) return false; const int idx = (c - 128) * 2 + i; u.pm = idx >> 2; u.pn = idx & 3; return true; }
; template <class Epi, class Sched, bool ALIGN_EPI = false, bool SP2 = false, bool F16 = false>
; __device__ __forceinline__ void gemm_phase(PG8_LAS unsigned char* lds, const Gemm g, const Sched& S, const Epi& E, const int wid_in) {
;     ...
;         const bool has_next = S.next(ui + 1, nxt);
;         const char* nA = has_next ? (const char*)g.A + (size_t)nxt.pm * tstep : cA; const char* nB = has_next ? (const char*)g.Bt + (size_t)nxt.pn * tstep : cB;
;     ...
; #pragma unroll
;         for (int a = 0; a < 2; ++a)
; #pragma unroll
;             for (int b = 0; b < 2; ++b)
; #pragma unroll
;                 for (int m = 0; m < 4; ++m)
; #pragma unroll
;                     for (int n = 0; n < 2; ++n) acc[a][b][m][n] = (f32x4){0.f, 0.f, 0.f, 0.f};
;         cur = nxt; cA = nA; cB = nB; ++ui;
.LBB0_2225:
	s_ashr_i32 s37, s36, 31
	s_lshl_b64 s[40:41], s[36:37], 19
	s_add_u32 s44, s59, s40
	s_addc_u32 s45, s60, s41
	s_and_b64 s[40:41], s[10:11], exec
	s_cselect_b32 s13, s45, s49
	s_cselect_b32 s23, s44, s48
	s_ashr_i32 s35, s34, 31
	s_lshl_b64 s[40:41], s[34:35], 19
	s_add_u32 s46, s61, s40
	s_addc_u32 s47, s62, s41
	s_and_b64 s[40:41], s[10:11], exec
	s_cselect_b32 s35, s47, s51
	s_cselect_b32 s37, s46, s50
	s_add_u32 s48, s48, 0x40080
	s_addc_u32 s49, s49, 0
	s_add_u32 s40, s50, 0x100
	v_mov_b32_e32 v0, 0
	s_addc_u32 s41, s51, 0
	s_mov_b32 s42, -2
	s_waitcnt lgkmcnt(0)
	v_mov_b32_e32 v1, v0
	v_mov_b32_e32 v2, v0
	v_mov_b32_e32 v3, v0
	v_mov_b32_e32 v4, v0
	v_mov_b32_e32 v5, v0
	v_mov_b32_e32 v6, v0
	v_mov_b32_e32 v7, v0
	v_mov_b32_e32 v16, v0
	v_mov_b32_e32 v17, v0
	v_mov_b32_e32 v18, v0
	v_mov_b32_e32 v19, v0
	v_mov_b32_e32 v20, v0
	v_mov_b32_e32 v21, v0
	v_mov_b32_e32 v22, v0
	v_mov_b32_e32 v23, v0
	v_mov_b32_e32 v32, v0
	v_mov_b32_e32 v33, v0
	v_mov_b32_e32 v34, v0
	v_mov_b32_e32 v35, v0
	v_mov_b32_e32 v36, v0
	v_mov_b32_e32 v37, v0
	v_mov_b32_e32 v38, v0
	v_mov_b32_e32 v39, v0
	v_mov_b32_e32 v48, v0
	v_mov_b32_e32 v49, v0
	v_mov_b32_e32 v50, v0
	v_mov_b32_e32 v51, v0
	v_mov_b32_e32 v52, v0
	v_mov_b32_e32 v53, v0
	v_mov_b32_e32 v54, v0
	v_mov_b32_e32 v55, v0
	v_mov_b32_e32 v8, v0
	v_mov_b32_e32 v9, v0
	v_mov_b32_e32 v10, v0
	v_mov_b32_e32 v11, v0
	v_mov_b32_e32 v12, v0
	v_mov_b32_e32 v13, v0
	v_mov_b32_e32 v14, v0
	v_mov_b32_e32 v15, v0
	v_mov_b32_e32 v24, v0
	v_mov_b32_e32 v25, v0
	v_mov_b32_e32 v26, v0
	v_mov_b32_e32 v27, v0
	v_mov_b32_e32 v28, v0
	v_mov_b32_e32 v29, v0
	v_mov_b32_e32 v30, v0
	v_mov_b32_e32 v31, v0
	v_mov_b32_e32 v40, v0
	v_mov_b32_e32 v41, v0
	v_mov_b32_e32 v42, v0
	v_mov_b32_e32 v43, v0
	v_mov_b32_e32 v44, v0
	v_mov_b32_e32 v45, v0
	v_mov_b32_e32 v46, v0
	v_mov_b32_e32 v47, v0
	v_mov_b32_e32 v56, v0
	v_mov_b32_e32 v57, v0
	v_mov_b32_e32 v58, v0
	v_mov_b32_e32 v59, v0
	v_mov_b32_e32 v60, v0
	v_mov_b32_e32 v61, v0
	v_mov_b32_e32 v62, v0
	v_mov_b32_e32 v63, v0
	v_mov_b32_e32 v64, v0
	v_mov_b32_e32 v65, v0
	v_mov_b32_e32 v66, v0
	v_mov_b32_e32 v67, v0
	v_mov_b32_e32 v68, v0
	v_mov_b32_e32 v69, v0
	v_mov_b32_e32 v70, v0
	v_mov_b32_e32 v71, v0
	v_mov_b32_e32 v80, v0
	v_mov_b32_e32 v81, v0
	v_mov_b32_e32 v82, v0
	v_mov_b32_e32 v83, v0
	v_mov_b32_e32 v84, v0
	v_mov_b32_e32 v85, v0
	v_mov_b32_e32 v86, v0
	v_mov_b32_e32 v87, v0
	v_mov_b32_e32 v96, v0
	v_mov_b32_e32 v97, v0
	v_mov_b32_e32 v98, v0
	v_mov_b32_e32 v99, v0
	v_mov_b32_e32 v100, v0
	v_mov_b32_e32 v101, v0
	v_mov_b32_e32 v102, v0
	v_mov_b32_e32 v103, v0
	v_mov_b32_e32 v112, v0
	v_mov_b32_e32 v113, v0
	v_mov_b32_e32 v114, v0
	v_mov_b32_e32 v115, v0
	v_mov_b32_e32 v116, v0
	v_mov_b32_e32 v117, v0
	v_mov_b32_e32 v118, v0
	v_mov_b32_e32 v119, v0
	v_mov_b32_e32 v72, v0
	v_mov_b32_e32 v73, v0
	v_mov_b32_e32 v74, v0
	v_mov_b32_e32 v75, v0
	v_mov_b32_e32 v76, v0
	v_mov_b32_e32 v77, v0
	v_mov_b32_e32 v78, v0
	v_mov_b32_e32 v79, v0
	v_mov_b32_e32 v88, v0
	v_mov_b32_e32 v89, v0
	v_mov_b32_e32 v90, v0
	v_mov_b32_e32 v91, v0
	v_mov_b32_e32 v92, v0
	v_mov_b32_e32 v93, v0
	v_mov_b32_e32 v94, v0
	v_mov_b32_e32 v95, v0
	v_mov_b32_e32 v104, v0
	v_mov_b32_e32 v105, v0
	v_mov_b32_e32 v106, v0
	v_mov_b32_e32 v107, v0
	v_mov_b32_e32 v108, v0
	v_mov_b32_e32 v109, v0
	v_mov_b32_e32 v110, v0
	v_mov_b32_e32 v111, v0
	v_mov_b32_e32 v120, v0
	v_mov_b32_e32 v121, v0
	v_mov_b32_e32 v122, v0
	v_mov_b32_e32 v123, v0
	v_mov_b32_e32 v124, v0
	v_mov_b32_e32 v125, v0
	v_mov_b32_e32 v126, v0
	v_mov_b32_e32 v127, v0
	s_cmp_lt_u32 s3, 4
	s_cbranch_scc0 .Lgsp_18
	s_setprio 1

;     __device__ __forceinline__ bool next(int i, pg8::Unit& u) const { if (c < 128 || i >= 2) return false; const int idx = (c - 128) * 2 + i; u.pm = idx >> 2; u.pn = idx & 3; return true; }
; template <class Epi, class Sched, bool ALIGN_EPI = false, bool SP2 = false, bool F16 = false>
; __device__ __forceinline__ void gemm_phase(PG8_LAS unsigned char* lds, const Gemm g, const Sched& S, const Epi& E, const int wid_in) {
;     ...
;         const bool has_next = S.next(ui + 1, nxt);
;         const char* nA = has_next ? (const char*)g.A + (size_t)nxt.pm * tstep : cA; const char* nB = has_next ? (const char*)g.Bt + (size_t)nxt.pn * tstep : cB;
;     ...
; #pragma unroll
;         for (int a = 0; a < 2; ++a)
; #pragma unroll
;             for (int b = 0; b < 2; ++b)
; #pragma unroll
;                 for (int m = 0; m < 4; ++m)
; #pragma unroll
;                     for (int n = 0; n < 2; ++n) acc[a][b][m][n] = (f32x4){0.f, 0.f, 0.f, 0.f};
;         cur = nxt; cA = nA; cB = nB; ++ui;
.LBB0_2488:
	s_ashr_i32 s29, s28, 31
	s_lshl_b64 s[30:31], s[28:29], 19
	s_add_u32 s30, s15, s30
	s_addc_u32 s31, s40, s31
	s_and_b64 s[34:35], s[10:11], exec
	s_cselect_b32 s29, s31, s43
	s_cselect_b32 s37, s30, s42
	s_ashr_i32 s27, s26, 31
	s_lshl_b64 s[34:35], s[26:27], 19
	s_add_u32 s34, s41, s34
	s_addc_u32 s35, s48, s35
	s_and_b64 s[46:47], s[10:11], exec
	s_cselect_b32 s27, s35, s45
	s_cselect_b32 s56, s34, s44
	s_add_u32 s42, s42, 0x40080
	s_addc_u32 s43, s43, 0
	s_add_u32 s57, s44, 0x100
	v_mov_b32_e32 v0, 0
	s_addc_u32 s58, s45, 0
	s_mov_b32 s59, -2
	v_mov_b32_e32 v1, v0
	v_mov_b32_e32 v2, v0
	v_mov_b32_e32 v3, v0
	v_mov_b32_e32 v4, v0
	v_mov_b32_e32 v5, v0
	v_mov_b32_e32 v6, v0
	v_mov_b32_e32 v7, v0
	v_mov_b32_e32 v16, v0
	v_mov_b32_e32 v17, v0
	v_mov_b32_e32 v18, v0
	v_mov_b32_e32 v19, v0
	v_mov_b32_e32 v20, v0
	v_mov_b32_e32 v21, v0
	v_mov_b32_e32 v22, v0
	v_mov_b32_e32 v23, v0
	v_mov_b32_e32 v32, v0
	v_mov_b32_e32 v33, v0
	v_mov_b32_e32 v34, v0
	v_mov_b32_e32 v35, v0
	v_mov_b32_e32 v36, v0
	v_mov_b32_e32 v37, v0
	v_mov_b32_e32 v38, v0
	v_mov_b32_e32 v39, v0
	v_mov_b32_e32 v48, v0
	v_mov_b32_e32 v49, v0
	v_mov_b32_e32 v50, v0
	v_mov_b32_e32 v51, v0
	v_mov_b32_e32 v52, v0
	v_mov_b32_e32 v53, v0
	v_mov_b32_e32 v54, v0
	v_mov_b32_e32 v55, v0
	v_mov_b32_e32 v8, v0
	v_mov_b32_e32 v9, v0
	v_mov_b32_e32 v10, v0
	v_mov_b32_e32 v11, v0
	v_mov_b32_e32 v12, v0
	v_mov_b32_e32 v13, v0
	v_mov_b32_e32 v14, v0
	v_mov_b32_e32 v15, v0
	v_mov_b32_e32 v24, v0
	v_mov_b32_e32 v25, v0
	v_mov_b32_e32 v26, v0
	v_mov_b32_e32 v27, v0
	v_mov_b32_e32 v28, v0
	v_mov_b32_e32 v29, v0
	v_mov_b32_e32 v30, v0
	v_mov_b32_e32 v31, v0
	v_mov_b32_e32 v40, v0
	v_mov_b32_e32 v41, v0
	v_mov_b32_e32 v42, v0
	v_mov_b32_e32 v43, v0
	v_mov_b32_e32 v44, v0
	v_mov_b32_e32 v45, v0
	v_mov_b32_e32 v46, v0
	v_mov_b32_e32 v47, v0
	v_mov_b32_e32 v56, v0
	v_mov_b32_e32 v57, v0
	v_mov_b32_e32 v58, v0
	v_mov_b32_e32 v59, v0
	v_mov_b32_e32 v60, v0
	v_mov_b32_e32 v61, v0
	v_mov_b32_e32 v62, v0
	v_mov_b32_e32 v63, v0
	v_mov_b32_e32 v64, v0
	v_mov_b32_e32 v65, v0
	v_mov_b32_e32 v66, v0
	v_mov_b32_e32 v67, v0
	v_mov_b32_e32 v68, v0
	v_mov_b32_e32 v69, v0
	v_mov_b32_e32 v70, v0
	v_mov_b32_e32 v71, v0
	v_mov_b32_e32 v80, v0
	v_mov_b32_e32 v81, v0
	v_mov_b32_e32 v82, v0
	v_mov_b32_e32 v83, v0
	v_mov_b32_e32 v84, v0
	v_mov_b32_e32 v85, v0
	v_mov_b32_e32 v86, v0
	v_mov_b32_e32 v87, v0
	v_mov_b32_e32 v96, v0
	v_mov_b32_e32 v97, v0
	v_mov_b32_e32 v98, v0
	v_mov_b32_e32 v99, v0
	v_mov_b32_e32 v100, v0
	v_mov_b32_e32 v101, v0
	v_mov_b32_e32 v102, v0
	v_mov_b32_e32 v103, v0
	v_mov_b32_e32 v112, v0
	v_mov_b32_e32 v113, v0
	v_mov_b32_e32 v114, v0
	v_mov_b32_e32 v115, v0
	v_mov_b32_e32 v116, v0
	v_mov_b32_e32 v117, v0
	v_mov_b32_e32 v118, v0
	v_mov_b32_e32 v119, v0
	v_mov_b32_e32 v72, v0
	v_mov_b32_e32 v73, v0
	v_mov_b32_e32 v74, v0
	v_mov_b32_e32 v75, v0
	v_mov_b32_e32 v76, v0
	v_mov_b32_e32 v77, v0
	v_mov_b32_e32 v78, v0
	v_mov_b32_e32 v79, v0
	v_mov_b32_e32 v88, v0
	v_mov_b32_e32 v89, v0
	v_mov_b32_e32 v90, v0
	v_mov_b32_e32 v91, v0
	v_mov_b32_e32 v92, v0
	v_mov_b32_e32 v93, v0
	v_mov_b32_e32 v94, v0
	v_mov_b32_e32 v95, v0
	v_mov_b32_e32 v104, v0
	v_mov_b32_e32 v105, v0
	v_mov_b32_e32 v106, v0
	v_mov_b32_e32 v107, v0
	v_mov_b32_e32 v108, v0
	v_mov_b32_e32 v109, v0
	v_mov_b32_e32 v110, v0
	v_mov_b32_e32 v111, v0
	v_mov_b32_e32 v120, v0
	v_mov_b32_e32 v121, v0
	v_mov_b32_e32 v122, v0
	v_mov_b32_e32 v123, v0
	v_mov_b32_e32 v124, v0
	v_mov_b32_e32 v125, v0
	v_mov_b32_e32 v126, v0
	v_mov_b32_e32 v127, v0
	s_cmp_lt_u32 s3, 4
	s_cbranch_scc0 .Lgsp_19
	s_setprio 1

;     __device__ __forceinline__ bool next(int i, pg8::Unit& u) const { if (c < 128 || i >= 2) return false; const int idx = (c - 128) * 2 + i; u.pm = idx >> 2; u.pn = idx & 3; return true; }
; template <class Epi, class Sched, bool ALIGN_EPI = false, bool SP2 = false, bool F16 = false>
; __device__ __forceinline__ void gemm_phase(PG8_LAS unsigned char* lds, const Gemm g, const Sched& S, const Epi& E, const int wid_in) {
;     ...
;         const bool has_next = S.next(ui + 1, nxt);
;         const char* nA = has_next ? (const char*)g.A + (size_t)nxt.pm * tstep : cA; const char* nB = has_next ? (const char*)g.Bt + (size_t)nxt.pn * tstep : cB;
;     ...
; #pragma unroll
;         for (int a = 0; a < 2; ++a)
; #pragma unroll
;             for (int b = 0; b < 2; ++b)
; #pragma unroll
;                 for (int m = 0; m < 4; ++m)
; #pragma unroll
;                     for (int n = 0; n < 2; ++n) acc[a][b][m][n] = (f32x4){0.f, 0.f, 0.f, 0.f};
;         cur = nxt; cA = nA; cB = nB; ++ui;
.LBB0_2565:
	s_ashr_i32 s25, s24, 31
	s_lshl_b64 s[26:27], s[24:25], 19
	s_add_u32 s26, s41, s26
	s_addc_u32 s27, s46, s27
	s_and_b64 s[28:29], s[10:11], exec
	s_cselect_b32 s25, s27, s37
	s_cselect_b32 s35, s26, s36
	s_ashr_i32 s23, s22, 31
	s_lshl_b64 s[28:29], s[22:23], 19
	s_add_u32 s28, s47, s28
	s_addc_u32 s29, s48, s29
	s_and_b64 s[44:45], s[10:11], exec
	s_cselect_b32 s23, s29, s43
	s_cselect_b32 s59, s28, s42
	s_add_u32 s36, s36, 0x40080
	s_addc_u32 s37, s37, 0
	s_add_u32 s60, s42, 0x100
	v_mov_b32_e32 v8, 0
	s_addc_u32 s61, s43, 0
	s_mov_b32 s62, -2
	v_mov_b32_e32 v9, v8
	v_mov_b32_e32 v10, v8
	v_mov_b32_e32 v11, v8
	v_mov_b32_e32 v12, v8
	v_mov_b32_e32 v13, v8
	v_mov_b32_e32 v14, v8
	v_mov_b32_e32 v15, v8
	v_mov_b32_e32 v24, v8
	v_mov_b32_e32 v25, v8
	v_mov_b32_e32 v26, v8
	v_mov_b32_e32 v27, v8
	v_mov_b32_e32 v28, v8
	v_mov_b32_e32 v29, v8
	v_mov_b32_e32 v30, v8
	v_mov_b32_e32 v31, v8
	v_mov_b32_e32 v40, v8
	v_mov_b32_e32 v41, v8
	v_mov_b32_e32 v42, v8
	v_mov_b32_e32 v43, v8
	v_mov_b32_e32 v44, v8
	v_mov_b32_e32 v45, v8
	v_mov_b32_e32 v46, v8
	v_mov_b32_e32 v47, v8
	v_mov_b32_e32 v56, v8
	v_mov_b32_e32 v57, v8
	v_mov_b32_e32 v58, v8
	v_mov_b32_e32 v59, v8
	v_mov_b32_e32 v60, v8
	v_mov_b32_e32 v61, v8
	v_mov_b32_e32 v62, v8
	v_mov_b32_e32 v63, v8
	v_mov_b32_e32 v16, v8
	v_mov_b32_e32 v17, v8
	v_mov_b32_e32 v18, v8
	v_mov_b32_e32 v19, v8
	v_mov_b32_e32 v20, v8
	v_mov_b32_e32 v21, v8
	v_mov_b32_e32 v22, v8
	v_mov_b32_e32 v23, v8
	v_mov_b32_e32 v32, v8
	v_mov_b32_e32 v33, v8
	v_mov_b32_e32 v34, v8
	v_mov_b32_e32 v35, v8
	v_mov_b32_e32 v36, v8
	v_mov_b32_e32 v37, v8
	v_mov_b32_e32 v38, v8
	v_mov_b32_e32 v39, v8
	v_mov_b32_e32 v48, v8
	v_mov_b32_e32 v49, v8
	v_mov_b32_e32 v50, v8
	v_mov_b32_e32 v51, v8
	v_mov_b32_e32 v52, v8
	v_mov_b32_e32 v53, v8
	v_mov_b32_e32 v54, v8
	v_mov_b32_e32 v55, v8
	v_mov_b32_e32 v64, v8
	v_mov_b32_e32 v65, v8
	v_mov_b32_e32 v66, v8
	v_mov_b32_e32 v67, v8
	v_mov_b32_e32 v68, v8
	v_mov_b32_e32 v69, v8
	v_mov_b32_e32 v70, v8
	v_mov_b32_e32 v71, v8
	v_mov_b32_e32 v72, v8
	v_mov_b32_e32 v73, v8
	v_mov_b32_e32 v74, v8
	v_mov_b32_e32 v75, v8
	v_mov_b32_e32 v76, v8
	v_mov_b32_e32 v77, v8
	v_mov_b32_e32 v78, v8
	v_mov_b32_e32 v79, v8
	v_mov_b32_e32 v88, v8
	v_mov_b32_e32 v89, v8
	v_mov_b32_e32 v90, v8
	v_mov_b32_e32 v91, v8
	v_mov_b32_e32 v92, v8
	v_mov_b32_e32 v93, v8
	v_mov_b32_e32 v94, v8
	v_mov_b32_e32 v95, v8
	v_mov_b32_e32 v104, v8
	v_mov_b32_e32 v105, v8
	v_mov_b32_e32 v106, v8
	v_mov_b32_e32 v107, v8
	v_mov_b32_e32 v108, v8
	v_mov_b32_e32 v109, v8
	v_mov_b32_e32 v110, v8
	v_mov_b32_e32 v111, v8
	v_mov_b32_e32 v120, v8
	v_mov_b32_e32 v121, v8
	v_mov_b32_e32 v122, v8
	v_mov_b32_e32 v123, v8
	v_mov_b32_e32 v124, v8
	v_mov_b32_e32 v125, v8
	v_mov_b32_e32 v126, v8
	v_mov_b32_e32 v127, v8
	v_mov_b32_e32 v80, v8
	v_mov_b32_e32 v81, v8
	v_mov_b32_e32 v82, v8
	v_mov_b32_e32 v83, v8
	v_mov_b32_e32 v84, v8
	v_mov_b32_e32 v85, v8
	v_mov_b32_e32 v86, v8
	v_mov_b32_e32 v87, v8
	v_mov_b32_e32 v96, v8
	v_mov_b32_e32 v97, v8
	v_mov_b32_e32 v98, v8
	v_mov_b32_e32 v99, v8
	v_mov_b32_e32 v100, v8
	v_mov_b32_e32 v101, v8
	v_mov_b32_e32 v102, v8
	v_mov_b32_e32 v103, v8
	v_mov_b32_e32 v112, v8
	v_mov_b32_e32 v113, v8
	v_mov_b32_e32 v114, v8
	v_mov_b32_e32 v115, v8
	v_mov_b32_e32 v116, v8
	v_mov_b32_e32 v117, v8
	v_mov_b32_e32 v118, v8
	v_mov_b32_e32 v119, v8
	v_mov_b32_e32 v128, v8
	v_mov_b32_e32 v129, v8
	v_mov_b32_e32 v130, v8
	v_mov_b32_e32 v131, v8
	v_mov_b32_e32 v132, v8
	v_mov_b32_e32 v133, v8
	v_mov_b32_e32 v134, v8
	v_mov_b32_e32 v135, v8
	s_cmp_lt_u32 s3, 4
	s_cbranch_scc0 .Lgsp_20
	s_setprio 1

;     __device__ __forceinline__ bool next(int i, pg8::Unit& u) const { if (c < 128 || i >= 2) return false; const int idx = (c - 128) * 2 + i; u.pm = idx >> 2; u.pn = idx & 3; return true; }
; template <class Epi, class Sched, bool ALIGN_EPI = false, bool SP2 = false, bool F16 = false>
; __device__ __forceinline__ void gemm_phase(PG8_LAS unsigned char* lds, const Gemm g, const Sched& S, const Epi& E, const int wid_in) {
;     ...
;         const bool has_next = S.next(ui + 1, nxt);
;         const char* nA = has_next ? (const char*)g.A + (size_t)nxt.pm * tstep : cA; const char* nB = has_next ? (const char*)g.Bt + (size_t)nxt.pn * tstep : cB;
;     ...
; #pragma unroll
;         for (int a = 0; a < 2; ++a)
; #pragma unroll
;             for (int b = 0; b < 2; ++b)
; #pragma unroll
;                 for (int m = 0; m < 4; ++m)
; #pragma unroll
;                     for (int n = 0; n < 2; ++n) acc[a][b][m][n] = (f32x4){0.f, 0.f, 0.f, 0.f};
;         cur = nxt; cA = nA; cB = nB; ++ui;
.LBB0_2696:
	s_add_u32 s53, s30, 0x100
	v_mov_b32_e32 v0, 0
	s_addc_u32 s54, s31, 0
	s_mov_b32 s55, -2
	v_mov_b32_e32 v1, v0
	v_mov_b32_e32 v2, v0
	v_mov_b32_e32 v3, v0
	v_mov_b32_e32 v4, v0
	v_mov_b32_e32 v5, v0
	v_mov_b32_e32 v6, v0
	v_mov_b32_e32 v7, v0
	v_mov_b32_e32 v16, v0
	v_mov_b32_e32 v17, v0
	v_mov_b32_e32 v18, v0
	v_mov_b32_e32 v19, v0
	v_mov_b32_e32 v20, v0
	v_mov_b32_e32 v21, v0
	v_mov_b32_e32 v22, v0
	v_mov_b32_e32 v23, v0
	v_mov_b32_e32 v32, v0
	v_mov_b32_e32 v33, v0
	v_mov_b32_e32 v34, v0
	v_mov_b32_e32 v35, v0
	v_mov_b32_e32 v36, v0
	v_mov_b32_e32 v37, v0
	v_mov_b32_e32 v38, v0
	v_mov_b32_e32 v39, v0
	v_mov_b32_e32 v48, v0
	v_mov_b32_e32 v49, v0
	v_mov_b32_e32 v50, v0
	v_mov_b32_e32 v51, v0
	v_mov_b32_e32 v52, v0
	v_mov_b32_e32 v53, v0
	v_mov_b32_e32 v54, v0
	v_mov_b32_e32 v55, v0
	v_mov_b32_e32 v8, v0
	v_mov_b32_e32 v9, v0
	v_mov_b32_e32 v10, v0
	v_mov_b32_e32 v11, v0
	v_mov_b32_e32 v12, v0
	v_mov_b32_e32 v13, v0
	v_mov_b32_e32 v14, v0
	v_mov_b32_e32 v15, v0
	v_mov_b32_e32 v24, v0
	v_mov_b32_e32 v25, v0
	v_mov_b32_e32 v26, v0
	v_mov_b32_e32 v27, v0
	v_mov_b32_e32 v28, v0
	v_mov_b32_e32 v29, v0
	v_mov_b32_e32 v30, v0
	v_mov_b32_e32 v31, v0
	v_mov_b32_e32 v40, v0
	v_mov_b32_e32 v41, v0
	v_mov_b32_e32 v42, v0
	v_mov_b32_e32 v43, v0
	v_mov_b32_e32 v44, v0
	v_mov_b32_e32 v45, v0
	v_mov_b32_e32 v46, v0
	v_mov_b32_e32 v47, v0
	v_mov_b32_e32 v56, v0
	v_mov_b32_e32 v57, v0
	v_mov_b32_e32 v58, v0
	v_mov_b32_e32 v59, v0
	v_mov_b32_e32 v60, v0
	v_mov_b32_e32 v61, v0
	v_mov_b32_e32 v62, v0
	v_mov_b32_e32 v63, v0
	v_mov_b32_e32 v64, v0
	v_mov_b32_e32 v65, v0
	v_mov_b32_e32 v66, v0
	v_mov_b32_e32 v67, v0
	v_mov_b32_e32 v68, v0
	v_mov_b32_e32 v69, v0
	v_mov_b32_e32 v70, v0
	v_mov_b32_e32 v71, v0
	v_mov_b32_e32 v80, v0
	v_mov_b32_e32 v81, v0
	v_mov_b32_e32 v82, v0
	v_mov_b32_e32 v83, v0
	v_mov_b32_e32 v84, v0
	v_mov_b32_e32 v85, v0
	v_mov_b32_e32 v86, v0
	v_mov_b32_e32 v87, v0
	v_mov_b32_e32 v96, v0
	v_mov_b32_e32 v97, v0
	v_mov_b32_e32 v98, v0
	v_mov_b32_e32 v99, v0
	v_mov_b32_e32 v100, v0
	v_mov_b32_e32 v101, v0
	v_mov_b32_e32 v102, v0
	v_mov_b32_e32 v103, v0
	v_mov_b32_e32 v112, v0
	v_mov_b32_e32 v113, v0
	v_mov_b32_e32 v114, v0
	v_mov_b32_e32 v115, v0
	v_mov_b32_e32 v116, v0
	v_mov_b32_e32 v117, v0
	v_mov_b32_e32 v118, v0
	v_mov_b32_e32 v119, v0
	v_mov_b32_e32 v72, v0
	v_mov_b32_e32 v73, v0
	v_mov_b32_e32 v74, v0
	v_mov_b32_e32 v75, v0
	v_mov_b32_e32 v76, v0
	v_mov_b32_e32 v77, v0
	v_mov_b32_e32 v78, v0
	v_mov_b32_e32 v79, v0
	v_mov_b32_e32 v88, v0
	v_mov_b32_e32 v89, v0
	v_mov_b32_e32 v90, v0
	v_mov_b32_e32 v91, v0
	v_mov_b32_e32 v92, v0
	v_mov_b32_e32 v93, v0
	v_mov_b32_e32 v94, v0
	v_mov_b32_e32 v95, v0
	v_mov_b32_e32 v104, v0
	v_mov_b32_e32 v105, v0
	v_mov_b32_e32 v106, v0
	v_mov_b32_e32 v107, v0
	v_mov_b32_e32 v108, v0
	v_mov_b32_e32 v109, v0
	v_mov_b32_e32 v110, v0
	v_mov_b32_e32 v111, v0
	v_mov_b32_e32 v120, v0
	v_mov_b32_e32 v121, v0
	v_mov_b32_e32 v122, v0
	v_mov_b32_e32 v123, v0
	v_mov_b32_e32 v124, v0
	v_mov_b32_e32 v125, v0
	v_mov_b32_e32 v126, v0
	v_mov_b32_e32 v127, v0
	s_cmp_lt_u32 s3, 4
	s_cbranch_scc0 .Lgsp_22
	s_setprio 1

;     __device__ __forceinline__ bool next(int i, pg8::Unit& u) const { if (c < 128 || i >= 2) return false; const int idx = (c - 128) * 2 + i; u.pm = idx >> 2; u.pn = idx & 3; return true; }
; template <class Epi, class Sched, bool ALIGN_EPI = false, bool SP2 = false, bool F16 = false>
; __device__ __forceinline__ void gemm_phase(PG8_LAS unsigned char* lds, const Gemm g, const Sched& S, const Epi& E, const int wid_in) {
;     ...
;         const bool has_next = S.next(ui + 1, nxt);
;         const char* nA = has_next ? (const char*)g.A + (size_t)nxt.pm * tstep : cA; const char* nB = has_next ? (const char*)g.Bt + (size_t)nxt.pn * tstep : cB;
;     ...
; #pragma unroll
;         for (int a = 0; a < 2; ++a)
; #pragma unroll
;             for (int b = 0; b < 2; ++b)
; #pragma unroll
;                 for (int m = 0; m < 4; ++m)
; #pragma unroll
;                     for (int n = 0; n < 2; ++n) acc[a][b][m][n] = (f32x4){0.f, 0.f, 0.f, 0.f};
;         cur = nxt; cA = nA; cB = nB; ++ui;
.LBB0_2792:
	s_ashr_i32 s31, s30, 31
	s_lshl_b64 s[14:15], s[30:31], 19
	s_add_u32 s34, s10, s14
	s_addc_u32 s35, s11, s15
	s_and_b64 s[14:15], s[8:9], exec
	s_cselect_b32 s14, s35, s43
	s_cselect_b32 s15, s34, s42
	s_ashr_i32 s29, s28, 31
	s_lshl_b64 s[36:37], s[28:29], 19
	s_add_u32 s36, s49, s36
	s_addc_u32 s37, s50, s37
	s_and_b64 s[46:47], s[8:9], exec
	s_cselect_b32 s29, s37, s45
	s_cselect_b32 s31, s36, s44
	s_add_u32 s42, s42, 0x40080
	s_addc_u32 s43, s43, 0
	s_add_u32 s41, s44, 0x100
	v_mov_b32_e32 v0, 0
	s_addc_u32 s58, s45, 0
	s_mov_b32 s59, -2
	v_mov_b32_e32 v1, v0
	v_mov_b32_e32 v2, v0
	v_mov_b32_e32 v3, v0
	v_mov_b32_e32 v4, v0
	v_mov_b32_e32 v5, v0
	v_mov_b32_e32 v6, v0
	v_mov_b32_e32 v7, v0
	v_mov_b32_e32 v16, v0
	v_mov_b32_e32 v17, v0
	v_mov_b32_e32 v18, v0
	v_mov_b32_e32 v19, v0
	v_mov_b32_e32 v20, v0
	v_mov_b32_e32 v21, v0
	v_mov_b32_e32 v22, v0
	v_mov_b32_e32 v23, v0
	v_mov_b32_e32 v32, v0
	v_mov_b32_e32 v33, v0
	v_mov_b32_e32 v34, v0
	v_mov_b32_e32 v35, v0
	v_mov_b32_e32 v36, v0
	v_mov_b32_e32 v37, v0
	v_mov_b32_e32 v38, v0
	v_mov_b32_e32 v39, v0
	v_mov_b32_e32 v48, v0
	v_mov_b32_e32 v49, v0
	v_mov_b32_e32 v50, v0
	v_mov_b32_e32 v51, v0
	v_mov_b32_e32 v52, v0
	v_mov_b32_e32 v53, v0
	v_mov_b32_e32 v54, v0
	v_mov_b32_e32 v55, v0
	v_mov_b32_e32 v8, v0
	v_mov_b32_e32 v9, v0
	v_mov_b32_e32 v10, v0
	v_mov_b32_e32 v11, v0
	v_mov_b32_e32 v12, v0
	v_mov_b32_e32 v13, v0
	v_mov_b32_e32 v14, v0
	v_mov_b32_e32 v15, v0
	v_mov_b32_e32 v24, v0
	v_mov_b32_e32 v25, v0
	v_mov_b32_e32 v26, v0
	v_mov_b32_e32 v27, v0
	v_mov_b32_e32 v28, v0
	v_mov_b32_e32 v29, v0
	v_mov_b32_e32 v30, v0
	v_mov_b32_e32 v31, v0
	v_mov_b32_e32 v40, v0
	v_mov_b32_e32 v41, v0
	v_mov_b32_e32 v42, v0
	v_mov_b32_e32 v43, v0
	v_mov_b32_e32 v44, v0
	v_mov_b32_e32 v45, v0
	v_mov_b32_e32 v46, v0
	v_mov_b32_e32 v47, v0
	v_mov_b32_e32 v56, v0
	v_mov_b32_e32 v57, v0
	v_mov_b32_e32 v58, v0
	v_mov_b32_e32 v59, v0
	v_mov_b32_e32 v60, v0
	v_mov_b32_e32 v61, v0
	v_mov_b32_e32 v62, v0
	v_mov_b32_e32 v63, v0
	v_mov_b32_e32 v64, v0
	v_mov_b32_e32 v65, v0
	v_mov_b32_e32 v66, v0
	v_mov_b32_e32 v67, v0
	v_mov_b32_e32 v68, v0
	v_mov_b32_e32 v69, v0
	v_mov_b32_e32 v70, v0
	v_mov_b32_e32 v71, v0
	v_mov_b32_e32 v80, v0
	v_mov_b32_e32 v81, v0
	v_mov_b32_e32 v82, v0
	v_mov_b32_e32 v83, v0
	v_mov_b32_e32 v84, v0
	v_mov_b32_e32 v85, v0
	v_mov_b32_e32 v86, v0
	v_mov_b32_e32 v87, v0
	v_mov_b32_e32 v96, v0
	v_mov_b32_e32 v97, v0
	v_mov_b32_e32 v98, v0
	v_mov_b32_e32 v99, v0
	v_mov_b32_e32 v100, v0
	v_mov_b32_e32 v101, v0
	v_mov_b32_e32 v102, v0
	v_mov_b32_e32 v103, v0
	v_mov_b32_e32 v120, v0
	v_mov_b32_e32 v121, v0
	v_mov_b32_e32 v122, v0
	v_mov_b32_e32 v123, v0
	v_mov_b32_e32 v124, v0
	v_mov_b32_e32 v125, v0
	v_mov_b32_e32 v126, v0
	v_mov_b32_e32 v127, v0
	v_mov_b32_e32 v72, v0
	v_mov_b32_e32 v73, v0
	v_mov_b32_e32 v74, v0
	v_mov_b32_e32 v75, v0
	v_mov_b32_e32 v76, v0
	v_mov_b32_e32 v77, v0
	v_mov_b32_e32 v78, v0
	v_mov_b32_e32 v79, v0
	v_mov_b32_e32 v88, v0
	v_mov_b32_e32 v89, v0
	v_mov_b32_e32 v90, v0
	v_mov_b32_e32 v91, v0
	v_mov_b32_e32 v92, v0
	v_mov_b32_e32 v93, v0
	v_mov_b32_e32 v94, v0
	v_mov_b32_e32 v95, v0
	v_mov_b32_e32 v104, v0
	v_mov_b32_e32 v105, v0
	v_mov_b32_e32 v106, v0
	v_mov_b32_e32 v107, v0
	v_mov_b32_e32 v108, v0
	v_mov_b32_e32 v109, v0
	v_mov_b32_e32 v110, v0
	v_mov_b32_e32 v111, v0
	v_mov_b32_e32 v136, v0
	v_mov_b32_e32 v137, v0
	v_mov_b32_e32 v138, v0
	v_mov_b32_e32 v139, v0
	v_mov_b32_e32 v140, v0
	v_mov_b32_e32 v141, v0
	v_mov_b32_e32 v142, v0
	v_mov_b32_e32 v143, v0
	s_cmp_lt_u32 s3, 4
	s_cbranch_scc0 .Lgsp_23
	s_setprio 1
